# up-proj without halo rows: 64x44 tiles of 256 tokens (11 per CU pair); rows above a tile fetched from the tile above through a published scratch slot + flag byte (system-scope stores/loads)
# speedup vs baseline: 1.1578x; 1.0147x over previous
.Lup_entry:
	s_waitcnt lgkmcnt(0)
	s_load_dwordx2 s[48:49], s[0:1], 0xc0
	s_load_dwordx2 s[50:51], s[0:1], 0xa8
	s_load_dwordx2 s[52:53], s[0:1], 0x108
	s_load_dwordx2 s[82:83], s[0:1], 0x78
	s_load_dwordx2 s[28:29], s[0:1], 0x80
	s_mov_b32 s59, 32
	s_mov_b32 s72, 0x100000
	s_mov_b32 s73, 0x58000
	s_movk_i32 s32, 0xbb0
	s_load_dwordx2 s[24:25], s[0:1], 0x110
	s_movk_i32 s32, 0xb00
	v_and_b32_e32 v0, 63, v154
	v_lshrrev_b32_e32 v131, 6, v154
	v_lshrrev_b32_e32 v243, 2, v0
	v_readfirstlane_b32 s41, v131
	v_and_b32_e32 v130, 3, v0
	v_mov_b32_e32 v134, 0x1320
	s_nop 1
	s_lshr_b32 s42, s41, 1
	s_and_b32 s43, s41, 1
	v_bfe_u32 v132, v0, 4, 2
	v_lshlrev_b32_e32 v132, 2, v132
	v_lshrrev_b32_e32 v132, v132, v134
	v_and_b32_e32 v132, 3, v132
	v_xor_b32_e32 v132, v132, v130
	v_lshlrev_b32_e32 v245, 4, v132
	v_bfe_u32 v132, v0, 2, 2
	v_lshlrev_b32_e32 v132, 2, v132
	v_lshrrev_b32_e32 v132, v132, v134
	v_and_b32_e32 v132, 3, v132
	v_lshrrev_b32_e32 v133, 4, v0
	v_xor_b32_e32 v132, v132, v133
	v_lshlrev_b32_e32 v132, 4, v132
	v_and_b32_e32 v131, 15, v0
	s_lshl_b32 s26, s42, 13
	v_lshl_add_u32 v238, v131, 6, v132
	v_add_u32_e32 v238, s26, v238
	s_lshl_b32 s62, s41, 12
	s_lshl_b32 s63, s41, 11
	s_add_i32 s63, s63, 0x4000
	s_lshl_b32 s26, s43, 12
	s_add_i32 s26, s26, 0x4000
	v_lshrrev_b32_e32 v134, 2, v131
	v_lshl_add_u32 v239, v134, 9, v132
	v_and_b32_e32 v134, 3, v131
	v_lshl_add_u32 v239, v134, 6, v239
	v_add_u32_e32 v239, s26, v239
	v_mov_b32_e32 v134, 0x1320
	v_lshrrev_b32_e32 v246, 3, v243
	v_and_b32_e32 v246, 3, v246
	v_lshlrev_b32_e32 v246, 2, v246
	v_lshrrev_b32_e32 v246, v246, v134
	v_and_b32_e32 v246, 3, v246
	v_xor_b32_e32 v246, v246, v130
	v_lshlrev_b32_e32 v246, 4, v246
	v_lshrrev_b32_e32 v247, 3, v243
	v_add_u32_e32 v247, 2, v247
	v_and_b32_e32 v247, 3, v247
	v_lshlrev_b32_e32 v247, 2, v247
	v_lshrrev_b32_e32 v247, v247, v134
	v_and_b32_e32 v247, 3, v247
	v_xor_b32_e32 v247, v247, v130
	v_lshlrev_b32_e32 v247, 4, v247
	s_lshl_b32 s26, s42, 7
	v_add_u32_e32 v227, s26, v131
	v_lshlrev_b32_e32 v134, 4, v133
	v_lshl_add_u32 v242, v227, 6, v134
	s_lshl_b32 s26, s43, 7
	v_lshl_add_u32 v228, v133, 5, s26
	s_mov_b32 s34, s3
	s_cmp_lt_i32 s34, s32
	s_cbranch_scc0 .Lup_done
	s_and_b32 s26, s34, 7
	s_lshr_b32 s27, s34, 3
	s_lshr_b32 s36, s27, 3
	s_and_b32 s27, s27, 7
	s_lshl_b32 s27, s27, 3
	s_add_i32 s35, s27, s26
	s_lshl_b32 s35, s35, 8
	s_lshl_b32 s36, s36, 7
	s_lshl_b32 s26, s41, 6
	s_add_i32 s26, s26, s35
	v_add_u32_e32 v0, s26, v243
	v_lshl_add_u32 v226, v0, 6, v245
	s_lshl_b32 s26, s41, 5
	s_add_i32 s26, s26, s36
	v_add_u32_e32 v0, s26, v243
	v_lshl_add_u32 v230, v0, 6, v246
	v_lshl_add_u32 v231, v0, 6, v247
	s_mov_b32 s60, 0
	s_mov_b32 s61, 0
	s_waitcnt lgkmcnt(0)
	s_and_b64 s[26:27], s[22:23], exec
	s_cselect_b32 s20, 2, 1
	s_cselect_b32 s26, 0x8400, 0
	s_cselect_b32 s27, 0x2c00, 0
	s_cmp_eq_u32 s41, 3
	s_cbranch_scc1 .Lup_wb
	s_mul_i32 s27, s41, 0x2c00
	s_add_i32 s26, s26, s27
	s_add_u32 s82, s82, s26
	s_addc_u32 s83, s83, 0
	s_branch .Lup_wd

.Lup_wd:
	s_mov_b32 s92, 0x3d372713
	s_mov_b32 s93, 0x3d372713
	s_mov_b32 s96, 0x3f4c422a
	s_mov_b32 s97, 0x3f4c422a
	s_mov_b32 s28, 0xc038aa3b
	s_mov_b32 s29, 0xc038aa3b
	s_mov_b64 s[54:55], s[48:49]
	s_mov_b64 s[56:57], s[50:51]
	s_add_i32 m0, s60, s62
	s_nop 0
	global_load_lds_dwordx4 v226, s[54:55]
	global_load_lds_dwordx4 v226, s[54:55] offset:1024
	global_load_lds_dwordx4 v226, s[54:55] offset:2048
	global_load_lds_dwordx4 v226, s[54:55] offset:3072
	s_add_i32 m0, s60, s63
	s_nop 0
	global_load_lds_dwordx4 v230, s[56:57]
	global_load_lds_dwordx4 v231, s[56:57] offset:1024
	s_add_i32 s60, s60, 0x6000
	s_cmp_eq_u32 s60, 0x12000
	s_cselect_b32 s60, 0, s60
	s_add_u32 s54, s54, s72
	s_addc_u32 s55, s55, 0
	s_add_u32 s56, s56, s73
	s_addc_u32 s57, s57, 0
	s_add_i32 m0, s60, s62
	s_nop 0
	global_load_lds_dwordx4 v226, s[54:55]
	global_load_lds_dwordx4 v226, s[54:55] offset:1024
	global_load_lds_dwordx4 v226, s[54:55] offset:2048
	global_load_lds_dwordx4 v226, s[54:55] offset:3072
	s_add_i32 m0, s60, s63
	s_nop 0
	global_load_lds_dwordx4 v230, s[56:57]
	global_load_lds_dwordx4 v231, s[56:57] offset:1024
	s_add_i32 s60, s60, 0x6000
	s_cmp_eq_u32 s60, 0x12000
	s_cselect_b32 s60, 0, s60
	s_add_u32 s54, s54, s72
	s_addc_u32 s55, s55, 0
	s_add_u32 s56, s56, s73
	s_addc_u32 s57, s57, 0
	s_add_i32 m0, s60, s62
	s_nop 0
	global_load_lds_dwordx4 v226, s[54:55]
	global_load_lds_dwordx4 v226, s[54:55] offset:1024
	global_load_lds_dwordx4 v226, s[54:55] offset:2048
	global_load_lds_dwordx4 v226, s[54:55] offset:3072
	s_add_i32 m0, s60, s63
	s_nop 0
	global_load_lds_dwordx4 v230, s[56:57]
	global_load_lds_dwordx4 v231, s[56:57] offset:1024
	s_add_i32 s60, s60, 0x6000
	s_cmp_eq_u32 s60, 0x12000
	s_cselect_b32 s60, 0, s60
	s_add_u32 s54, s54, s72
	s_addc_u32 s55, s55, 0
	s_add_u32 s56, s56, s73
	s_addc_u32 s57, s57, 0
	s_waitcnt vmcnt(12)
	s_barrier
	v_add_u32_e32 v240, s61, v238
	v_add_u32_e32 v241, s61, v239
	ds_read_b128 v[162:165], v241 offset:0
	ds_read_b128 v[166:169], v241 offset:256
	ds_read_b128 v[170:173], v241 offset:2048
	ds_read_b128 v[174:177], v241 offset:2304
	ds_read_b128 v[130:133], v240 offset:0
	ds_read_b128 v[134:137], v240 offset:1024
	ds_read_b128 v[138:141], v240 offset:2048
	ds_read_b128 v[142:145], v240 offset:3072
	ds_read_b128 v[146:149], v240 offset:4096
	ds_read_b128 v[150:153], v240 offset:5120
	ds_read_b128 v[154:157], v240 offset:6144
	ds_read_b128 v[158:161], v240 offset:7168
	s_add_i32 s61, s61, 0x6000
	s_cmp_eq_u32 s61, 0x12000
	s_cselect_b32 s61, 0, s61
	s_add_i32 s38, s34, s71
	s_cmp_lt_i32 s38, s32
	s_cselect_b32 s37, 1, 0
	s_cbranch_scc0 .Lup_nn_a
	s_and_b32 s26, s38, 7
	s_lshr_b32 s27, s38, 3
	s_lshr_b32 s31, s27, 3
	s_and_b32 s27, s27, 7
	s_lshl_b32 s27, s27, 3
	s_add_i32 s30, s27, s26
	s_lshl_b32 s30, s30, 8
	s_lshl_b32 s31, s31, 7
	s_lshl_b32 s26, s41, 6
	s_add_i32 s26, s26, s30
	v_add_u32_e32 v0, s26, v243
	v_lshl_add_u32 v232, v0, 6, v245
	s_lshl_b32 s26, s41, 5
	s_add_i32 s26, s26, s31
	v_add_u32_e32 v0, s26, v243
	v_lshl_add_u32 v236, v0, 6, v246
	v_lshl_add_u32 v237, v0, 6, v247
.Lup_nn_a:
	s_waitcnt vmcnt(6) lgkmcnt(0)
	s_barrier
	v_add_u32_e32 v240, s61, v238
	v_add_u32_e32 v241, s61, v239
	s_add_i32 m0, s60, s62
	v_mfma_f32_16x16x32_bf16 v[2:5], v[162:165], v[130:133], 0
	global_load_lds_dwordx4 v226, s[54:55]
	v_mfma_f32_16x16x32_bf16 v[6:9], v[166:169], v[130:133], 0
	global_load_lds_dwordx4 v226, s[54:55] offset:1024
	v_mfma_f32_16x16x32_bf16 v[10:13], v[170:173], v[130:133], 0
	global_load_lds_dwordx4 v226, s[54:55] offset:2048
	v_mfma_f32_16x16x32_bf16 v[14:17], v[174:177], v[130:133], 0
	global_load_lds_dwordx4 v226, s[54:55] offset:3072
	s_add_i32 m0, s60, s63
	v_mfma_f32_16x16x32_bf16 v[18:21], v[162:165], v[134:137], 0
	global_load_lds_dwordx4 v230, s[56:57]
	v_mfma_f32_16x16x32_bf16 v[22:25], v[166:169], v[134:137], 0
	global_load_lds_dwordx4 v231, s[56:57] offset:1024
	v_mfma_f32_16x16x32_bf16 v[26:29], v[170:173], v[134:137], 0
	v_mfma_f32_16x16x32_bf16 v[30:33], v[174:177], v[134:137], 0
	v_mfma_f32_16x16x32_bf16 v[34:37], v[162:165], v[138:141], 0
	ds_read_b128 v[210:213], v241 offset:0
	v_mfma_f32_16x16x32_bf16 v[38:41], v[166:169], v[138:141], 0
	ds_read_b128 v[214:217], v241 offset:256
	v_mfma_f32_16x16x32_bf16 v[42:45], v[170:173], v[138:141], 0
	ds_read_b128 v[218:221], v241 offset:2048
	v_mfma_f32_16x16x32_bf16 v[46:49], v[174:177], v[138:141], 0
	ds_read_b128 v[222:225], v241 offset:2304
	v_mfma_f32_16x16x32_bf16 v[50:53], v[162:165], v[142:145], 0
	ds_read_b128 v[178:181], v240 offset:0
	v_mfma_f32_16x16x32_bf16 v[54:57], v[166:169], v[142:145], 0
	ds_read_b128 v[182:185], v240 offset:1024
	v_mfma_f32_16x16x32_bf16 v[58:61], v[170:173], v[142:145], 0
	ds_read_b128 v[186:189], v240 offset:2048
	v_mfma_f32_16x16x32_bf16 v[62:65], v[174:177], v[142:145], 0
	ds_read_b128 v[190:193], v240 offset:3072
	v_mfma_f32_16x16x32_bf16 v[66:69], v[162:165], v[146:149], 0
	ds_read_b128 v[194:197], v240 offset:4096
	v_mfma_f32_16x16x32_bf16 v[70:73], v[166:169], v[146:149], 0
	ds_read_b128 v[198:201], v240 offset:5120
	v_mfma_f32_16x16x32_bf16 v[74:77], v[170:173], v[146:149], 0
	ds_read_b128 v[202:205], v240 offset:6144
	v_mfma_f32_16x16x32_bf16 v[78:81], v[174:177], v[146:149], 0
	ds_read_b128 v[206:209], v240 offset:7168
	s_setprio 1
	v_mfma_f32_16x16x32_bf16 v[82:85], v[162:165], v[150:153], 0
	v_mfma_f32_16x16x32_bf16 v[86:89], v[166:169], v[150:153], 0
	v_mfma_f32_16x16x32_bf16 v[90:93], v[170:173], v[150:153], 0
	v_mfma_f32_16x16x32_bf16 v[94:97], v[174:177], v[150:153], 0
	v_mfma_f32_16x16x32_bf16 v[98:101], v[162:165], v[154:157], 0
	v_mfma_f32_16x16x32_bf16 v[102:105], v[166:169], v[154:157], 0
	v_mfma_f32_16x16x32_bf16 v[106:109], v[170:173], v[154:157], 0
	v_mfma_f32_16x16x32_bf16 v[110:113], v[174:177], v[154:157], 0
	v_mfma_f32_16x16x32_bf16 v[114:117], v[162:165], v[158:161], 0
	v_mfma_f32_16x16x32_bf16 v[118:121], v[166:169], v[158:161], 0
	v_mfma_f32_16x16x32_bf16 v[122:125], v[170:173], v[158:161], 0
	v_mfma_f32_16x16x32_bf16 v[126:129], v[174:177], v[158:161], 0
	s_setprio 0
	s_add_i32 s60, s60, 0x6000
	s_cmp_eq_u32 s60, 0x12000
	s_cselect_b32 s60, 0, s60
	s_add_u32 s54, s54, s72
	s_addc_u32 s55, s55, 0
	s_add_u32 s56, s56, s73
	s_addc_u32 s57, s57, 0
	s_add_i32 s61, s61, 0x6000
	s_cmp_eq_u32 s61, 0x12000
	s_cselect_b32 s61, 0, s61
	v_mbcnt_lo_u32_b32 v0, -1, 0
	v_lshlrev_b32_e32 v0, 4, v0
	s_lshl_b32 s26, s36, 1
	v_add_u32_e32 v0, s26, v0
	s_lshl_b32 s26, s41, 8
	s_add_i32 m0, s26, 0x13010
	s_mov_b64 exec, 0xffff
	global_load_lds_dwordx4 v0, s[82:83]
	s_mov_b64 exec, -1
	s_waitcnt vmcnt(6) lgkmcnt(0)
	s_barrier
	v_add_u32_e32 v240, s61, v238
	v_add_u32_e32 v241, s61, v239
	s_add_i32 m0, s60, s62
	v_mfma_f32_16x16x32_bf16 v[2:5], v[210:213], v[178:181], v[2:5]
	global_load_lds_dwordx4 v226, s[54:55]
	v_mfma_f32_16x16x32_bf16 v[6:9], v[214:217], v[178:181], v[6:9]
	global_load_lds_dwordx4 v226, s[54:55] offset:1024
	v_mfma_f32_16x16x32_bf16 v[10:13], v[218:221], v[178:181], v[10:13]
	global_load_lds_dwordx4 v226, s[54:55] offset:2048
	v_mfma_f32_16x16x32_bf16 v[14:17], v[222:225], v[178:181], v[14:17]
	global_load_lds_dwordx4 v226, s[54:55] offset:3072
	s_add_i32 m0, s60, s63
	v_mfma_f32_16x16x32_bf16 v[18:21], v[210:213], v[182:185], v[18:21]
	global_load_lds_dwordx4 v230, s[56:57]
	v_mfma_f32_16x16x32_bf16 v[22:25], v[214:217], v[182:185], v[22:25]
	global_load_lds_dwordx4 v231, s[56:57] offset:1024
	v_mfma_f32_16x16x32_bf16 v[26:29], v[218:221], v[182:185], v[26:29]
	v_mfma_f32_16x16x32_bf16 v[30:33], v[222:225], v[182:185], v[30:33]
	v_mfma_f32_16x16x32_bf16 v[34:37], v[210:213], v[186:189], v[34:37]
	ds_read_b128 v[162:165], v241 offset:0
	v_mfma_f32_16x16x32_bf16 v[38:41], v[214:217], v[186:189], v[38:41]
	ds_read_b128 v[166:169], v241 offset:256
	v_mfma_f32_16x16x32_bf16 v[42:45], v[218:221], v[186:189], v[42:45]
	ds_read_b128 v[170:173], v241 offset:2048
	v_mfma_f32_16x16x32_bf16 v[46:49], v[222:225], v[186:189], v[46:49]
	ds_read_b128 v[174:177], v241 offset:2304
	v_mfma_f32_16x16x32_bf16 v[50:53], v[210:213], v[190:193], v[50:53]
	ds_read_b128 v[130:133], v240 offset:0
	v_mfma_f32_16x16x32_bf16 v[54:57], v[214:217], v[190:193], v[54:57]
	ds_read_b128 v[134:137], v240 offset:1024
	v_mfma_f32_16x16x32_bf16 v[58:61], v[218:221], v[190:193], v[58:61]
	ds_read_b128 v[138:141], v240 offset:2048
	v_mfma_f32_16x16x32_bf16 v[62:65], v[222:225], v[190:193], v[62:65]
	ds_read_b128 v[142:145], v240 offset:3072
	v_mfma_f32_16x16x32_bf16 v[66:69], v[210:213], v[194:197], v[66:69]
	ds_read_b128 v[146:149], v240 offset:4096
	v_mfma_f32_16x16x32_bf16 v[70:73], v[214:217], v[194:197], v[70:73]
	ds_read_b128 v[150:153], v240 offset:5120
	v_mfma_f32_16x16x32_bf16 v[74:77], v[218:221], v[194:197], v[74:77]
	ds_read_b128 v[154:157], v240 offset:6144
	v_mfma_f32_16x16x32_bf16 v[78:81], v[222:225], v[194:197], v[78:81]
	ds_read_b128 v[158:161], v240 offset:7168
	s_setprio 1
	v_mfma_f32_16x16x32_bf16 v[82:85], v[210:213], v[198:201], v[82:85]
	v_mfma_f32_16x16x32_bf16 v[86:89], v[214:217], v[198:201], v[86:89]
	v_mfma_f32_16x16x32_bf16 v[90:93], v[218:221], v[198:201], v[90:93]
	v_mfma_f32_16x16x32_bf16 v[94:97], v[222:225], v[198:201], v[94:97]
	v_mfma_f32_16x16x32_bf16 v[98:101], v[210:213], v[202:205], v[98:101]
	v_mfma_f32_16x16x32_bf16 v[102:105], v[214:217], v[202:205], v[102:105]
	v_mfma_f32_16x16x32_bf16 v[106:109], v[218:221], v[202:205], v[106:109]
	v_mfma_f32_16x16x32_bf16 v[110:113], v[222:225], v[202:205], v[110:113]
	v_mfma_f32_16x16x32_bf16 v[114:117], v[210:213], v[206:209], v[114:117]
	v_mfma_f32_16x16x32_bf16 v[118:121], v[214:217], v[206:209], v[118:121]
	v_mfma_f32_16x16x32_bf16 v[122:125], v[218:221], v[206:209], v[122:125]
	v_mfma_f32_16x16x32_bf16 v[126:129], v[222:225], v[206:209], v[126:129]
	s_setprio 0
	s_add_i32 s60, s60, 0x6000
	s_cmp_eq_u32 s60, 0x12000
	s_cselect_b32 s60, 0, s60
	s_add_u32 s54, s54, s72
	s_addc_u32 s55, s55, 0
	s_add_u32 s56, s56, s73
	s_addc_u32 s57, s57, 0
	s_add_i32 s61, s61, 0x6000
	s_cmp_eq_u32 s61, 0x12000
	s_cselect_b32 s61, 0, s61
	s_branch .Lup_main
.Lup_tile:
	s_add_i32 s38, s34, s71
	s_cmp_lt_i32 s38, s32
	s_cselect_b32 s37, 1, 0
	s_cbranch_scc0 .Lup_nn_b
	s_and_b32 s26, s38, 7
	s_lshr_b32 s27, s38, 3
	s_lshr_b32 s31, s27, 3
	s_and_b32 s27, s27, 7
	s_lshl_b32 s27, s27, 3
	s_add_i32 s30, s27, s26
	s_lshl_b32 s30, s30, 8
	s_lshl_b32 s31, s31, 7
	s_lshl_b32 s26, s41, 6
	s_add_i32 s26, s26, s30
	v_add_u32_e32 v0, s26, v243
	v_lshl_add_u32 v232, v0, 6, v245
	s_lshl_b32 s26, s41, 5
	s_add_i32 s26, s26, s31
	v_add_u32_e32 v0, s26, v243
	v_lshl_add_u32 v236, v0, 6, v246
	v_lshl_add_u32 v237, v0, 6, v247
.Lup_nn_b:
	s_waitcnt vmcnt(14) lgkmcnt(0)
	s_barrier
	v_add_u32_e32 v240, s61, v238
	v_add_u32_e32 v241, s61, v239
	s_add_i32 m0, s60, s62
	v_mfma_f32_16x16x32_bf16 v[2:5], v[162:165], v[130:133], 0
	global_load_lds_dwordx4 v226, s[54:55]
	v_mfma_f32_16x16x32_bf16 v[6:9], v[166:169], v[130:133], 0
	global_load_lds_dwordx4 v226, s[54:55] offset:1024
	v_mfma_f32_16x16x32_bf16 v[10:13], v[170:173], v[130:133], 0
	global_load_lds_dwordx4 v226, s[54:55] offset:2048
	v_mfma_f32_16x16x32_bf16 v[14:17], v[174:177], v[130:133], 0
	global_load_lds_dwordx4 v226, s[54:55] offset:3072
	s_add_i32 m0, s60, s63
	v_mfma_f32_16x16x32_bf16 v[18:21], v[162:165], v[134:137], 0
	global_load_lds_dwordx4 v230, s[56:57]
	v_mfma_f32_16x16x32_bf16 v[22:25], v[166:169], v[134:137], 0
	global_load_lds_dwordx4 v231, s[56:57] offset:1024
	v_mfma_f32_16x16x32_bf16 v[26:29], v[170:173], v[134:137], 0
	v_mfma_f32_16x16x32_bf16 v[30:33], v[174:177], v[134:137], 0
	v_mfma_f32_16x16x32_bf16 v[34:37], v[162:165], v[138:141], 0
	ds_read_b128 v[210:213], v241 offset:0
	v_mfma_f32_16x16x32_bf16 v[38:41], v[166:169], v[138:141], 0
	ds_read_b128 v[214:217], v241 offset:256
	v_mfma_f32_16x16x32_bf16 v[42:45], v[170:173], v[138:141], 0
	ds_read_b128 v[218:221], v241 offset:2048
	v_mfma_f32_16x16x32_bf16 v[46:49], v[174:177], v[138:141], 0
	ds_read_b128 v[222:225], v241 offset:2304
	v_mfma_f32_16x16x32_bf16 v[50:53], v[162:165], v[142:145], 0
	ds_read_b128 v[178:181], v240 offset:0
	v_mfma_f32_16x16x32_bf16 v[54:57], v[166:169], v[142:145], 0
	ds_read_b128 v[182:185], v240 offset:1024
	v_mfma_f32_16x16x32_bf16 v[58:61], v[170:173], v[142:145], 0
	ds_read_b128 v[186:189], v240 offset:2048
	v_mfma_f32_16x16x32_bf16 v[62:65], v[174:177], v[142:145], 0
	ds_read_b128 v[190:193], v240 offset:3072
	v_mfma_f32_16x16x32_bf16 v[66:69], v[162:165], v[146:149], 0
	ds_read_b128 v[194:197], v240 offset:4096
	v_mfma_f32_16x16x32_bf16 v[70:73], v[166:169], v[146:149], 0
	ds_read_b128 v[198:201], v240 offset:5120
	v_mfma_f32_16x16x32_bf16 v[74:77], v[170:173], v[146:149], 0
	ds_read_b128 v[202:205], v240 offset:6144
	v_mfma_f32_16x16x32_bf16 v[78:81], v[174:177], v[146:149], 0
	ds_read_b128 v[206:209], v240 offset:7168
	s_setprio 1
	v_mfma_f32_16x16x32_bf16 v[82:85], v[162:165], v[150:153], 0
	v_mfma_f32_16x16x32_bf16 v[86:89], v[166:169], v[150:153], 0
	v_mfma_f32_16x16x32_bf16 v[90:93], v[170:173], v[150:153], 0
	v_mfma_f32_16x16x32_bf16 v[94:97], v[174:177], v[150:153], 0
	v_mfma_f32_16x16x32_bf16 v[98:101], v[162:165], v[154:157], 0
	v_mfma_f32_16x16x32_bf16 v[102:105], v[166:169], v[154:157], 0
	v_mfma_f32_16x16x32_bf16 v[106:109], v[170:173], v[154:157], 0
	v_mfma_f32_16x16x32_bf16 v[110:113], v[174:177], v[154:157], 0
	v_mfma_f32_16x16x32_bf16 v[114:117], v[162:165], v[158:161], 0
	v_mfma_f32_16x16x32_bf16 v[118:121], v[166:169], v[158:161], 0
	v_mfma_f32_16x16x32_bf16 v[122:125], v[170:173], v[158:161], 0
	v_mfma_f32_16x16x32_bf16 v[126:129], v[174:177], v[158:161], 0
	s_setprio 0
	s_add_i32 s60, s60, 0x6000
	s_cmp_eq_u32 s60, 0x12000
	s_cselect_b32 s60, 0, s60
	s_add_u32 s54, s54, s72
	s_addc_u32 s55, s55, 0
	s_add_u32 s56, s56, s73
	s_addc_u32 s57, s57, 0
	s_add_i32 s61, s61, 0x6000
	s_cmp_eq_u32 s61, 0x12000
	s_cselect_b32 s61, 0, s61
	v_mbcnt_lo_u32_b32 v0, -1, 0
	v_lshlrev_b32_e32 v0, 4, v0
	s_lshl_b32 s26, s36, 1
	v_add_u32_e32 v0, s26, v0
	s_lshl_b32 s26, s41, 8
	s_add_i32 m0, s26, 0x13010
	s_mov_b64 exec, 0xffff
	global_load_lds_dwordx4 v0, s[82:83]
	s_mov_b64 exec, -1
	s_waitcnt vmcnt(14) lgkmcnt(0)
	s_barrier
	v_add_u32_e32 v240, s61, v238
	v_add_u32_e32 v241, s61, v239
	s_add_i32 m0, s60, s62
	v_mfma_f32_16x16x32_bf16 v[2:5], v[210:213], v[178:181], v[2:5]
	global_load_lds_dwordx4 v226, s[54:55]
	v_mfma_f32_16x16x32_bf16 v[6:9], v[214:217], v[178:181], v[6:9]
	global_load_lds_dwordx4 v226, s[54:55] offset:1024
	v_mfma_f32_16x16x32_bf16 v[10:13], v[218:221], v[178:181], v[10:13]
	global_load_lds_dwordx4 v226, s[54:55] offset:2048
	v_mfma_f32_16x16x32_bf16 v[14:17], v[222:225], v[178:181], v[14:17]
	global_load_lds_dwordx4 v226, s[54:55] offset:3072
	s_add_i32 m0, s60, s63
	v_mfma_f32_16x16x32_bf16 v[18:21], v[210:213], v[182:185], v[18:21]
	global_load_lds_dwordx4 v230, s[56:57]
	v_mfma_f32_16x16x32_bf16 v[22:25], v[214:217], v[182:185], v[22:25]
	global_load_lds_dwordx4 v231, s[56:57] offset:1024
	v_mfma_f32_16x16x32_bf16 v[26:29], v[218:221], v[182:185], v[26:29]
	v_mfma_f32_16x16x32_bf16 v[30:33], v[222:225], v[182:185], v[30:33]
	v_mfma_f32_16x16x32_bf16 v[34:37], v[210:213], v[186:189], v[34:37]
	ds_read_b128 v[162:165], v241 offset:0
	v_mfma_f32_16x16x32_bf16 v[38:41], v[214:217], v[186:189], v[38:41]
	ds_read_b128 v[166:169], v241 offset:256
	v_mfma_f32_16x16x32_bf16 v[42:45], v[218:221], v[186:189], v[42:45]
	ds_read_b128 v[170:173], v241 offset:2048
	v_mfma_f32_16x16x32_bf16 v[46:49], v[222:225], v[186:189], v[46:49]
	ds_read_b128 v[174:177], v241 offset:2304
	v_mfma_f32_16x16x32_bf16 v[50:53], v[210:213], v[190:193], v[50:53]
	ds_read_b128 v[130:133], v240 offset:0
	v_mfma_f32_16x16x32_bf16 v[54:57], v[214:217], v[190:193], v[54:57]
	ds_read_b128 v[134:137], v240 offset:1024
	v_mfma_f32_16x16x32_bf16 v[58:61], v[218:221], v[190:193], v[58:61]
	ds_read_b128 v[138:141], v240 offset:2048
	v_mfma_f32_16x16x32_bf16 v[62:65], v[222:225], v[190:193], v[62:65]
	ds_read_b128 v[142:145], v240 offset:3072
	v_mfma_f32_16x16x32_bf16 v[66:69], v[210:213], v[194:197], v[66:69]
	ds_read_b128 v[146:149], v240 offset:4096
	v_mfma_f32_16x16x32_bf16 v[70:73], v[214:217], v[194:197], v[70:73]
	ds_read_b128 v[150:153], v240 offset:5120
	v_mfma_f32_16x16x32_bf16 v[74:77], v[218:221], v[194:197], v[74:77]
	ds_read_b128 v[154:157], v240 offset:6144
	v_mfma_f32_16x16x32_bf16 v[78:81], v[222:225], v[194:197], v[78:81]
	ds_read_b128 v[158:161], v240 offset:7168
	s_setprio 1
	v_mfma_f32_16x16x32_bf16 v[82:85], v[210:213], v[198:201], v[82:85]
	v_mfma_f32_16x16x32_bf16 v[86:89], v[214:217], v[198:201], v[86:89]
	v_mfma_f32_16x16x32_bf16 v[90:93], v[218:221], v[198:201], v[90:93]
	v_mfma_f32_16x16x32_bf16 v[94:97], v[222:225], v[198:201], v[94:97]
	v_mfma_f32_16x16x32_bf16 v[98:101], v[210:213], v[202:205], v[98:101]
	v_mfma_f32_16x16x32_bf16 v[102:105], v[214:217], v[202:205], v[102:105]
	v_mfma_f32_16x16x32_bf16 v[106:109], v[218:221], v[202:205], v[106:109]
	v_mfma_f32_16x16x32_bf16 v[110:113], v[222:225], v[202:205], v[110:113]
	v_mfma_f32_16x16x32_bf16 v[114:117], v[210:213], v[206:209], v[114:117]
	v_mfma_f32_16x16x32_bf16 v[118:121], v[214:217], v[206:209], v[118:121]
	v_mfma_f32_16x16x32_bf16 v[122:125], v[218:221], v[206:209], v[122:125]
	v_mfma_f32_16x16x32_bf16 v[126:129], v[222:225], v[206:209], v[126:129]
	s_setprio 0
	s_add_i32 s60, s60, 0x6000
	s_cmp_eq_u32 s60, 0x12000
	s_cselect_b32 s60, 0, s60
	s_add_u32 s54, s54, s72
	s_addc_u32 s55, s55, 0
	s_add_u32 s56, s56, s73
	s_addc_u32 s57, s57, 0
	s_add_i32 s61, s61, 0x6000
	s_cmp_eq_u32 s61, 0x12000
	s_cselect_b32 s61, 0, s61

.Lup_kdone:
	s_cmp_eq_u32 s37, 0
	s_cbranch_scc1 .Lup_tail_last
	s_waitcnt vmcnt(6) lgkmcnt(0)
	s_barrier
	v_add_u32_e32 v240, s61, v238
	v_add_u32_e32 v241, s61, v239
	s_add_i32 m0, s60, s62
	v_mfma_f32_16x16x32_bf16 v[2:5], v[162:165], v[130:133], v[2:5]
	global_load_lds_dwordx4 v226, s[54:55]
	v_mfma_f32_16x16x32_bf16 v[6:9], v[166:169], v[130:133], v[6:9]
	global_load_lds_dwordx4 v226, s[54:55] offset:1024
	v_mfma_f32_16x16x32_bf16 v[10:13], v[170:173], v[130:133], v[10:13]
	global_load_lds_dwordx4 v226, s[54:55] offset:2048
	v_mfma_f32_16x16x32_bf16 v[14:17], v[174:177], v[130:133], v[14:17]
	global_load_lds_dwordx4 v226, s[54:55] offset:3072
	s_add_i32 m0, s60, s63
	v_mfma_f32_16x16x32_bf16 v[18:21], v[162:165], v[134:137], v[18:21]
	global_load_lds_dwordx4 v230, s[56:57]
	v_mfma_f32_16x16x32_bf16 v[22:25], v[166:169], v[134:137], v[22:25]
	global_load_lds_dwordx4 v231, s[56:57] offset:1024
	v_mfma_f32_16x16x32_bf16 v[26:29], v[170:173], v[134:137], v[26:29]
	v_mfma_f32_16x16x32_bf16 v[30:33], v[174:177], v[134:137], v[30:33]
	v_mfma_f32_16x16x32_bf16 v[34:37], v[162:165], v[138:141], v[34:37]
	ds_read_b128 v[210:213], v241 offset:0
	v_mfma_f32_16x16x32_bf16 v[38:41], v[166:169], v[138:141], v[38:41]
	ds_read_b128 v[214:217], v241 offset:256
	v_mfma_f32_16x16x32_bf16 v[42:45], v[170:173], v[138:141], v[42:45]
	ds_read_b128 v[218:221], v241 offset:2048
	v_mfma_f32_16x16x32_bf16 v[46:49], v[174:177], v[138:141], v[46:49]
	ds_read_b128 v[222:225], v241 offset:2304
	v_mfma_f32_16x16x32_bf16 v[50:53], v[162:165], v[142:145], v[50:53]
	ds_read_b128 v[178:181], v240 offset:0
	v_mfma_f32_16x16x32_bf16 v[54:57], v[166:169], v[142:145], v[54:57]
	ds_read_b128 v[182:185], v240 offset:1024
	v_mfma_f32_16x16x32_bf16 v[58:61], v[170:173], v[142:145], v[58:61]
	ds_read_b128 v[186:189], v240 offset:2048
	v_mfma_f32_16x16x32_bf16 v[62:65], v[174:177], v[142:145], v[62:65]
	ds_read_b128 v[190:193], v240 offset:3072
	v_mfma_f32_16x16x32_bf16 v[66:69], v[162:165], v[146:149], v[66:69]
	ds_read_b128 v[194:197], v240 offset:4096
	v_mfma_f32_16x16x32_bf16 v[70:73], v[166:169], v[146:149], v[70:73]
	ds_read_b128 v[198:201], v240 offset:5120
	v_mfma_f32_16x16x32_bf16 v[74:77], v[170:173], v[146:149], v[74:77]
	ds_read_b128 v[202:205], v240 offset:6144
	v_mfma_f32_16x16x32_bf16 v[78:81], v[174:177], v[146:149], v[78:81]
	ds_read_b128 v[206:209], v240 offset:7168
	s_setprio 1
	v_mfma_f32_16x16x32_bf16 v[82:85], v[162:165], v[150:153], v[82:85]
	v_mfma_f32_16x16x32_bf16 v[86:89], v[166:169], v[150:153], v[86:89]
	v_mfma_f32_16x16x32_bf16 v[90:93], v[170:173], v[150:153], v[90:93]
	v_mfma_f32_16x16x32_bf16 v[94:97], v[174:177], v[150:153], v[94:97]
	v_mfma_f32_16x16x32_bf16 v[98:101], v[162:165], v[154:157], v[98:101]
	v_mfma_f32_16x16x32_bf16 v[102:105], v[166:169], v[154:157], v[102:105]
	v_mfma_f32_16x16x32_bf16 v[106:109], v[170:173], v[154:157], v[106:109]
	v_mfma_f32_16x16x32_bf16 v[110:113], v[174:177], v[154:157], v[110:113]
	v_mfma_f32_16x16x32_bf16 v[114:117], v[162:165], v[158:161], v[114:117]
	v_mfma_f32_16x16x32_bf16 v[118:121], v[166:169], v[158:161], v[118:121]
	v_mfma_f32_16x16x32_bf16 v[122:125], v[170:173], v[158:161], v[122:125]
	v_mfma_f32_16x16x32_bf16 v[126:129], v[174:177], v[158:161], v[126:129]
	s_setprio 0
	s_add_i32 s60, s60, 0x6000
	s_cmp_eq_u32 s60, 0x12000
	s_cselect_b32 s60, 0, s60
	s_add_u32 s54, s54, s72
	s_addc_u32 s55, s55, 0
	s_add_u32 s56, s56, s73
	s_addc_u32 s57, s57, 0
	s_add_i32 s61, s61, 0x6000
	s_cmp_eq_u32 s61, 0x12000
	s_cselect_b32 s61, 0, s61
	v_mov_b32_e32 v226, v232
	v_mov_b32_e32 v230, v236
	v_mov_b32_e32 v231, v237
	s_mov_b64 s[54:55], s[48:49]
	s_mov_b64 s[56:57], s[50:51]
	s_waitcnt vmcnt(6) lgkmcnt(0)
	s_barrier
	v_add_u32_e32 v240, s61, v238
	v_add_u32_e32 v241, s61, v239
	s_add_i32 m0, s60, s62
	v_mfma_f32_16x16x32_bf16 v[2:5], v[210:213], v[178:181], v[2:5]
	global_load_lds_dwordx4 v226, s[54:55]
	v_mfma_f32_16x16x32_bf16 v[6:9], v[214:217], v[178:181], v[6:9]
	global_load_lds_dwordx4 v226, s[54:55] offset:1024
	v_mfma_f32_16x16x32_bf16 v[10:13], v[218:221], v[178:181], v[10:13]
	global_load_lds_dwordx4 v226, s[54:55] offset:2048
	v_mfma_f32_16x16x32_bf16 v[14:17], v[222:225], v[178:181], v[14:17]
	global_load_lds_dwordx4 v226, s[54:55] offset:3072
	s_add_i32 m0, s60, s63
	v_mfma_f32_16x16x32_bf16 v[18:21], v[210:213], v[182:185], v[18:21]
	global_load_lds_dwordx4 v230, s[56:57]
	v_mfma_f32_16x16x32_bf16 v[22:25], v[214:217], v[182:185], v[22:25]
	global_load_lds_dwordx4 v231, s[56:57] offset:1024
	v_mfma_f32_16x16x32_bf16 v[26:29], v[218:221], v[182:185], v[26:29]
	v_mfma_f32_16x16x32_bf16 v[30:33], v[222:225], v[182:185], v[30:33]
	v_mfma_f32_16x16x32_bf16 v[34:37], v[210:213], v[186:189], v[34:37]
	ds_read_b128 v[162:165], v241 offset:0
	v_mfma_f32_16x16x32_bf16 v[38:41], v[214:217], v[186:189], v[38:41]
	ds_read_b128 v[166:169], v241 offset:256
	v_mfma_f32_16x16x32_bf16 v[42:45], v[218:221], v[186:189], v[42:45]
	ds_read_b128 v[170:173], v241 offset:2048
	v_mfma_f32_16x16x32_bf16 v[46:49], v[222:225], v[186:189], v[46:49]
	ds_read_b128 v[174:177], v241 offset:2304
	v_mfma_f32_16x16x32_bf16 v[50:53], v[210:213], v[190:193], v[50:53]
	ds_read_b128 v[130:133], v240 offset:0
	v_mfma_f32_16x16x32_bf16 v[54:57], v[214:217], v[190:193], v[54:57]
	ds_read_b128 v[134:137], v240 offset:1024
	v_mfma_f32_16x16x32_bf16 v[58:61], v[218:221], v[190:193], v[58:61]
	ds_read_b128 v[138:141], v240 offset:2048
	v_mfma_f32_16x16x32_bf16 v[62:65], v[222:225], v[190:193], v[62:65]
	ds_read_b128 v[142:145], v240 offset:3072
	v_mfma_f32_16x16x32_bf16 v[66:69], v[210:213], v[194:197], v[66:69]
	ds_read_b128 v[146:149], v240 offset:4096
	v_mfma_f32_16x16x32_bf16 v[70:73], v[214:217], v[194:197], v[70:73]
	ds_read_b128 v[150:153], v240 offset:5120
	v_mfma_f32_16x16x32_bf16 v[74:77], v[218:221], v[194:197], v[74:77]
	ds_read_b128 v[154:157], v240 offset:6144
	v_mfma_f32_16x16x32_bf16 v[78:81], v[222:225], v[194:197], v[78:81]
	ds_read_b128 v[158:161], v240 offset:7168
	s_setprio 1
	v_mfma_f32_16x16x32_bf16 v[82:85], v[210:213], v[198:201], v[82:85]
	v_mfma_f32_16x16x32_bf16 v[86:89], v[214:217], v[198:201], v[86:89]
	v_mfma_f32_16x16x32_bf16 v[90:93], v[218:221], v[198:201], v[90:93]
	v_mfma_f32_16x16x32_bf16 v[94:97], v[222:225], v[198:201], v[94:97]
	v_mfma_f32_16x16x32_bf16 v[98:101], v[210:213], v[202:205], v[98:101]
	v_mfma_f32_16x16x32_bf16 v[102:105], v[214:217], v[202:205], v[102:105]
	v_mfma_f32_16x16x32_bf16 v[106:109], v[218:221], v[202:205], v[106:109]
	v_mfma_f32_16x16x32_bf16 v[110:113], v[222:225], v[202:205], v[110:113]
	v_mfma_f32_16x16x32_bf16 v[114:117], v[210:213], v[206:209], v[114:117]
	v_mfma_f32_16x16x32_bf16 v[118:121], v[214:217], v[206:209], v[118:121]
	v_mfma_f32_16x16x32_bf16 v[122:125], v[218:221], v[206:209], v[122:125]
	v_mfma_f32_16x16x32_bf16 v[126:129], v[222:225], v[206:209], v[126:129]
	s_setprio 0
	s_add_i32 s60, s60, 0x6000
	s_cmp_eq_u32 s60, 0x12000
	s_cselect_b32 s60, 0, s60
	s_add_u32 s54, s54, s72
	s_addc_u32 s55, s55, 0
	s_add_u32 s56, s56, s73
	s_addc_u32 s57, s57, 0
	s_add_i32 s61, s61, 0x6000
	s_cmp_eq_u32 s61, 0x12000
	s_cselect_b32 s61, 0, s61
	s_waitcnt vmcnt(6) lgkmcnt(0)
	s_barrier
	v_add_u32_e32 v240, s61, v238
	v_add_u32_e32 v241, s61, v239
	s_add_i32 m0, s60, s62
	v_mfma_f32_16x16x32_bf16 v[2:5], v[162:165], v[130:133], v[2:5]
	global_load_lds_dwordx4 v226, s[54:55]
	v_mfma_f32_16x16x32_bf16 v[6:9], v[166:169], v[130:133], v[6:9]
	global_load_lds_dwordx4 v226, s[54:55] offset:1024
	v_mfma_f32_16x16x32_bf16 v[10:13], v[170:173], v[130:133], v[10:13]
	global_load_lds_dwordx4 v226, s[54:55] offset:2048
	v_mfma_f32_16x16x32_bf16 v[14:17], v[174:177], v[130:133], v[14:17]
	global_load_lds_dwordx4 v226, s[54:55] offset:3072
	s_add_i32 m0, s60, s63
	v_mfma_f32_16x16x32_bf16 v[18:21], v[162:165], v[134:137], v[18:21]
	global_load_lds_dwordx4 v230, s[56:57]
	v_mfma_f32_16x16x32_bf16 v[22:25], v[166:169], v[134:137], v[22:25]
	global_load_lds_dwordx4 v231, s[56:57] offset:1024
	v_mfma_f32_16x16x32_bf16 v[26:29], v[170:173], v[134:137], v[26:29]
	v_mfma_f32_16x16x32_bf16 v[30:33], v[174:177], v[134:137], v[30:33]
	v_mfma_f32_16x16x32_bf16 v[34:37], v[162:165], v[138:141], v[34:37]
	ds_read_b128 v[210:213], v241 offset:0
	v_mfma_f32_16x16x32_bf16 v[38:41], v[166:169], v[138:141], v[38:41]
	ds_read_b128 v[214:217], v241 offset:256
	v_mfma_f32_16x16x32_bf16 v[42:45], v[170:173], v[138:141], v[42:45]
	ds_read_b128 v[218:221], v241 offset:2048
	v_mfma_f32_16x16x32_bf16 v[46:49], v[174:177], v[138:141], v[46:49]
	ds_read_b128 v[222:225], v241 offset:2304
	v_mfma_f32_16x16x32_bf16 v[50:53], v[162:165], v[142:145], v[50:53]
	ds_read_b128 v[178:181], v240 offset:0
	v_mfma_f32_16x16x32_bf16 v[54:57], v[166:169], v[142:145], v[54:57]
	ds_read_b128 v[182:185], v240 offset:1024
	v_mfma_f32_16x16x32_bf16 v[58:61], v[170:173], v[142:145], v[58:61]
	ds_read_b128 v[186:189], v240 offset:2048
	v_mfma_f32_16x16x32_bf16 v[62:65], v[174:177], v[142:145], v[62:65]
	ds_read_b128 v[190:193], v240 offset:3072
	v_mfma_f32_16x16x32_bf16 v[66:69], v[162:165], v[146:149], v[66:69]
	ds_read_b128 v[194:197], v240 offset:4096
	v_mfma_f32_16x16x32_bf16 v[70:73], v[166:169], v[146:149], v[70:73]
	ds_read_b128 v[198:201], v240 offset:5120
	v_mfma_f32_16x16x32_bf16 v[74:77], v[170:173], v[146:149], v[74:77]
	ds_read_b128 v[202:205], v240 offset:6144
	v_mfma_f32_16x16x32_bf16 v[78:81], v[174:177], v[146:149], v[78:81]
	ds_read_b128 v[206:209], v240 offset:7168
	s_setprio 1
	v_mfma_f32_16x16x32_bf16 v[82:85], v[162:165], v[150:153], v[82:85]
	v_mfma_f32_16x16x32_bf16 v[86:89], v[166:169], v[150:153], v[86:89]
	v_mfma_f32_16x16x32_bf16 v[90:93], v[170:173], v[150:153], v[90:93]
	v_mfma_f32_16x16x32_bf16 v[94:97], v[174:177], v[150:153], v[94:97]
	v_mfma_f32_16x16x32_bf16 v[98:101], v[162:165], v[154:157], v[98:101]
	v_mfma_f32_16x16x32_bf16 v[102:105], v[166:169], v[154:157], v[102:105]
	v_mfma_f32_16x16x32_bf16 v[106:109], v[170:173], v[154:157], v[106:109]
	v_mfma_f32_16x16x32_bf16 v[110:113], v[174:177], v[154:157], v[110:113]
	v_mfma_f32_16x16x32_bf16 v[114:117], v[162:165], v[158:161], v[114:117]
	v_mfma_f32_16x16x32_bf16 v[118:121], v[166:169], v[158:161], v[118:121]
	v_mfma_f32_16x16x32_bf16 v[122:125], v[170:173], v[158:161], v[122:125]
	v_mfma_f32_16x16x32_bf16 v[126:129], v[174:177], v[158:161], v[126:129]
	s_setprio 0
	s_add_i32 s60, s60, 0x6000
	s_cmp_eq_u32 s60, 0x12000
	s_cselect_b32 s60, 0, s60
	s_add_u32 s54, s54, s72
	s_addc_u32 s55, s55, 0
	s_add_u32 s56, s56, s73
	s_addc_u32 s57, s57, 0
	s_add_i32 s61, s61, 0x6000
	s_cmp_eq_u32 s61, 0x12000
	s_cselect_b32 s61, 0, s61
	s_waitcnt vmcnt(6) lgkmcnt(0)
	s_barrier
	v_add_u32_e32 v240, s61, v238
	v_add_u32_e32 v241, s61, v239
	s_add_i32 m0, s60, s62
	v_mfma_f32_16x16x32_bf16 v[2:5], v[210:213], v[178:181], v[2:5]
	global_load_lds_dwordx4 v226, s[54:55]
	v_mfma_f32_16x16x32_bf16 v[6:9], v[214:217], v[178:181], v[6:9]
	global_load_lds_dwordx4 v226, s[54:55] offset:1024
	v_mfma_f32_16x16x32_bf16 v[10:13], v[218:221], v[178:181], v[10:13]
	global_load_lds_dwordx4 v226, s[54:55] offset:2048
	v_mfma_f32_16x16x32_bf16 v[14:17], v[222:225], v[178:181], v[14:17]
	global_load_lds_dwordx4 v226, s[54:55] offset:3072
	s_add_i32 m0, s60, s63
	v_mfma_f32_16x16x32_bf16 v[18:21], v[210:213], v[182:185], v[18:21]
	global_load_lds_dwordx4 v230, s[56:57]
	v_mfma_f32_16x16x32_bf16 v[22:25], v[214:217], v[182:185], v[22:25]
	global_load_lds_dwordx4 v231, s[56:57] offset:1024
	v_mfma_f32_16x16x32_bf16 v[26:29], v[218:221], v[182:185], v[26:29]
	v_mfma_f32_16x16x32_bf16 v[30:33], v[222:225], v[182:185], v[30:33]
	v_mfma_f32_16x16x32_bf16 v[34:37], v[210:213], v[186:189], v[34:37]
	ds_read_b128 v[162:165], v241 offset:0
	v_mfma_f32_16x16x32_bf16 v[38:41], v[214:217], v[186:189], v[38:41]
	ds_read_b128 v[166:169], v241 offset:256
	v_mfma_f32_16x16x32_bf16 v[42:45], v[218:221], v[186:189], v[42:45]
	ds_read_b128 v[170:173], v241 offset:2048
	v_mfma_f32_16x16x32_bf16 v[46:49], v[222:225], v[186:189], v[46:49]
	ds_read_b128 v[174:177], v241 offset:2304
	v_mfma_f32_16x16x32_bf16 v[50:53], v[210:213], v[190:193], v[50:53]
	ds_read_b128 v[130:133], v240 offset:0
	v_mfma_f32_16x16x32_bf16 v[54:57], v[214:217], v[190:193], v[54:57]
	ds_read_b128 v[134:137], v240 offset:1024
	v_mfma_f32_16x16x32_bf16 v[58:61], v[218:221], v[190:193], v[58:61]
	ds_read_b128 v[138:141], v240 offset:2048
	v_mfma_f32_16x16x32_bf16 v[62:65], v[222:225], v[190:193], v[62:65]
	ds_read_b128 v[142:145], v240 offset:3072
	v_mfma_f32_16x16x32_bf16 v[66:69], v[210:213], v[194:197], v[66:69]
	ds_read_b128 v[146:149], v240 offset:4096
	v_mfma_f32_16x16x32_bf16 v[70:73], v[214:217], v[194:197], v[70:73]
	ds_read_b128 v[150:153], v240 offset:5120
	v_mfma_f32_16x16x32_bf16 v[74:77], v[218:221], v[194:197], v[74:77]
	ds_read_b128 v[154:157], v240 offset:6144
	v_mfma_f32_16x16x32_bf16 v[78:81], v[222:225], v[194:197], v[78:81]
	ds_read_b128 v[158:161], v240 offset:7168
	s_setprio 1
	v_mfma_f32_16x16x32_bf16 v[82:85], v[210:213], v[198:201], v[82:85]
	v_mfma_f32_16x16x32_bf16 v[86:89], v[214:217], v[198:201], v[86:89]
	v_mfma_f32_16x16x32_bf16 v[90:93], v[218:221], v[198:201], v[90:93]
	v_mfma_f32_16x16x32_bf16 v[94:97], v[222:225], v[198:201], v[94:97]
	v_mfma_f32_16x16x32_bf16 v[98:101], v[210:213], v[202:205], v[98:101]
	v_mfma_f32_16x16x32_bf16 v[102:105], v[214:217], v[202:205], v[102:105]
	v_mfma_f32_16x16x32_bf16 v[106:109], v[218:221], v[202:205], v[106:109]
	v_mfma_f32_16x16x32_bf16 v[110:113], v[222:225], v[202:205], v[110:113]
	v_mfma_f32_16x16x32_bf16 v[114:117], v[210:213], v[206:209], v[114:117]
	v_mfma_f32_16x16x32_bf16 v[118:121], v[214:217], v[206:209], v[118:121]
	v_mfma_f32_16x16x32_bf16 v[122:125], v[218:221], v[206:209], v[122:125]
	v_mfma_f32_16x16x32_bf16 v[126:129], v[222:225], v[206:209], v[126:129]
	s_setprio 0
	s_add_i32 s60, s60, 0x6000
	s_cmp_eq_u32 s60, 0x12000
	s_cselect_b32 s60, 0, s60
	s_add_u32 s54, s54, s72
	s_addc_u32 s55, s55, 0
	s_add_u32 s56, s56, s73
	s_addc_u32 s57, s57, 0
	s_add_i32 s61, s61, 0x6000
	s_cmp_eq_u32 s61, 0x12000
	s_cselect_b32 s61, 0, s61
	s_and_b32 s39, s35, 0xfff
	s_lshr_b32 s21, s36, 7
	s_waitcnt vmcnt(18)
	v_mbcnt_lo_u32_b32 v217, -1, 0
	v_mbcnt_hi_u32_b32 v217, -1, v217
	v_lshlrev_b32_e32 v217, 5, v217
	s_lshl_b32 s26, s43, 11
	v_add_u32_e32 v248, s26, v217
	s_add_i32 s26, s26, 0x12010
	v_add_u32_e32 v217, s26, v217
	s_cmp_eq_u32 s42, 0
	s_cbranch_scc0 .Lup_en_nowr
	ds_write_b128 v217, v[114:117]
	ds_write_b128 v217, v[118:121] offset:16
	s_branch .Lup_en_wrd
.Lup_en_nowr:
	s_lshl_b32 s26, s34, 12
	v_add_u32_e32 v249, s26, v248
	global_store_dwordx4 v249, v[114:117], s[24:25] sc0 sc1
	global_store_dwordx4 v249, v[118:121], s[24:25] offset:16 sc0 sc1

.Lup_en_cont:
	v_add_u32_e32 v216, 0x13010, v228
	ds_read_b128 v[178:181], v216 offset:0
	ds_read_b128 v[182:185], v216 offset:16
	ds_read_b128 v[186:189], v216 offset:256
	ds_read_b128 v[190:193], v216 offset:272
	ds_read_b128 v[194:197], v216 offset:512
	ds_read_b128 v[198:201], v216 offset:528
	ds_read_b128 v[202:205], v216 offset:768
	ds_read_b128 v[206:209], v216 offset:784
	s_lshl_b32 s26, s21, 1
	s_add_i32 s26, s26, s43
	s_lshl_b32 s26, s26, 20
	s_lshl_b32 s27, s35, 6
	s_add_u32 s18, s52, s26
	s_addc_u32 s19, s53, 0
	s_add_u32 s18, s18, s27
	s_addc_u32 s19, s19, 0
	s_add_u32 s6, s18, 0x1000
	s_addc_u32 s7, s19, 0
	s_waitcnt lgkmcnt(0)
	v_mov_b32_dpp v210, v98 row_ror:1 row_mask:0xf bank_mask:0xf
	v_mov_b32_dpp v212, v98 row_ror:2 row_mask:0xf bank_mask:0xf
	v_mov_b32_dpp v211, v99 row_ror:1 row_mask:0xf bank_mask:0xf
	v_mov_b32_dpp v213, v99 row_ror:2 row_mask:0xf bank_mask:0xf
	s_nop 1
	v_mov_b32_dpp v210, v114 row_shr:1 row_mask:0xf bank_mask:0xf
	v_mov_b32_dpp v212, v114 row_shr:2 row_mask:0xf bank_mask:0xf
	v_mov_b32_dpp v211, v115 row_shr:1 row_mask:0xf bank_mask:0xf
	v_mov_b32_dpp v213, v115 row_shr:2 row_mask:0xf bank_mask:0xf
	s_nop 1
	v_pk_mul_f32 v[210:211], v[186:187], v[210:211]
	v_pk_fma_f32 v[214:215], v[194:195], v[114:115], v[210:211]
	v_pk_fma_f32 v[214:215], v[178:179], v[212:213], v[214:215]
	v_pk_add_f32 v[214:215], v[202:203], v[214:215]
	v_pk_mul_f32 v[216:217], v[214:215], s[92:93]
	v_pk_mul_f32 v[216:217], v[214:215], v[216:217]
	v_pk_fma_f32 v[216:217], v[214:215], v[216:217], v[214:215]
	v_pk_mul_f32 v[216:217], v[216:217], s[96:97]
	v_pk_mul_f32 v[216:217], v[216:217], s[28:29]
	v_exp_f32_e32 v216, v216
	v_exp_f32_e32 v217, v217
	s_nop 0
	v_add_f32_e32 v216, 1.0, v216
	v_add_f32_e32 v217, 1.0, v217
	v_rcp_f32_e32 v216, v216
	v_rcp_f32_e32 v217, v217
	s_nop 0
	v_pk_mul_f32 v[214:215], v[214:215], v[216:217]
	v_pk_mul_f32 v[214:215], v[122:123], v[214:215]
	v_cvt_pk_bf16_f32 v122, v214, v215
	v_mov_b32_dpp v210, v100 row_ror:1 row_mask:0xf bank_mask:0xf
	v_mov_b32_dpp v212, v100 row_ror:2 row_mask:0xf bank_mask:0xf
	v_mov_b32_dpp v211, v101 row_ror:1 row_mask:0xf bank_mask:0xf
	v_mov_b32_dpp v213, v101 row_ror:2 row_mask:0xf bank_mask:0xf
	s_nop 1
	v_mov_b32_dpp v210, v116 row_shr:1 row_mask:0xf bank_mask:0xf
	v_mov_b32_dpp v212, v116 row_shr:2 row_mask:0xf bank_mask:0xf
	v_mov_b32_dpp v211, v117 row_shr:1 row_mask:0xf bank_mask:0xf
	v_mov_b32_dpp v213, v117 row_shr:2 row_mask:0xf bank_mask:0xf
	s_nop 1
	v_pk_mul_f32 v[210:211], v[188:189], v[210:211]
	v_pk_fma_f32 v[214:215], v[196:197], v[116:117], v[210:211]
	v_pk_fma_f32 v[214:215], v[180:181], v[212:213], v[214:215]
	v_pk_add_f32 v[214:215], v[204:205], v[214:215]
	v_pk_mul_f32 v[216:217], v[214:215], s[92:93]
	v_pk_mul_f32 v[216:217], v[214:215], v[216:217]
	v_pk_fma_f32 v[216:217], v[214:215], v[216:217], v[214:215]
	v_pk_mul_f32 v[216:217], v[216:217], s[96:97]
	v_pk_mul_f32 v[216:217], v[216:217], s[28:29]
	v_exp_f32_e32 v216, v216
	v_exp_f32_e32 v217, v217
	s_nop 0
	v_add_f32_e32 v216, 1.0, v216
	v_add_f32_e32 v217, 1.0, v217
	v_rcp_f32_e32 v216, v216
	v_rcp_f32_e32 v217, v217
	s_nop 0
	v_pk_mul_f32 v[214:215], v[214:215], v[216:217]
	v_pk_mul_f32 v[214:215], v[124:125], v[214:215]
	v_cvt_pk_bf16_f32 v123, v214, v215
	v_mov_b32_dpp v210, v102 row_ror:1 row_mask:0xf bank_mask:0xf
	v_mov_b32_dpp v212, v102 row_ror:2 row_mask:0xf bank_mask:0xf
	v_mov_b32_dpp v211, v103 row_ror:1 row_mask:0xf bank_mask:0xf
	v_mov_b32_dpp v213, v103 row_ror:2 row_mask:0xf bank_mask:0xf
	s_nop 1
	v_mov_b32_dpp v210, v118 row_shr:1 row_mask:0xf bank_mask:0xf
	v_mov_b32_dpp v212, v118 row_shr:2 row_mask:0xf bank_mask:0xf
	v_mov_b32_dpp v211, v119 row_shr:1 row_mask:0xf bank_mask:0xf
	v_mov_b32_dpp v213, v119 row_shr:2 row_mask:0xf bank_mask:0xf
	s_nop 1
	v_pk_mul_f32 v[210:211], v[190:191], v[210:211]
	v_pk_fma_f32 v[214:215], v[198:199], v[118:119], v[210:211]
	v_pk_fma_f32 v[214:215], v[182:183], v[212:213], v[214:215]
	v_pk_add_f32 v[214:215], v[206:207], v[214:215]
	v_pk_mul_f32 v[216:217], v[214:215], s[92:93]
	v_pk_mul_f32 v[216:217], v[214:215], v[216:217]
	v_pk_fma_f32 v[216:217], v[214:215], v[216:217], v[214:215]
	v_pk_mul_f32 v[216:217], v[216:217], s[96:97]
	v_pk_mul_f32 v[216:217], v[216:217], s[28:29]
	v_exp_f32_e32 v216, v216
	v_exp_f32_e32 v217, v217
	s_nop 0
	v_add_f32_e32 v216, 1.0, v216
	v_add_f32_e32 v217, 1.0, v217
	v_rcp_f32_e32 v216, v216
	v_rcp_f32_e32 v217, v217
	s_nop 0
	v_pk_mul_f32 v[214:215], v[214:215], v[216:217]
	v_pk_mul_f32 v[214:215], v[126:127], v[214:215]
	v_cvt_pk_bf16_f32 v124, v214, v215
	v_mov_b32_dpp v210, v104 row_ror:1 row_mask:0xf bank_mask:0xf
	v_mov_b32_dpp v212, v104 row_ror:2 row_mask:0xf bank_mask:0xf
	v_mov_b32_dpp v211, v105 row_ror:1 row_mask:0xf bank_mask:0xf
	v_mov_b32_dpp v213, v105 row_ror:2 row_mask:0xf bank_mask:0xf
	s_nop 1
	v_mov_b32_dpp v210, v120 row_shr:1 row_mask:0xf bank_mask:0xf
	v_mov_b32_dpp v212, v120 row_shr:2 row_mask:0xf bank_mask:0xf
	v_mov_b32_dpp v211, v121 row_shr:1 row_mask:0xf bank_mask:0xf
	v_mov_b32_dpp v213, v121 row_shr:2 row_mask:0xf bank_mask:0xf
	s_nop 1
	v_pk_mul_f32 v[210:211], v[192:193], v[210:211]
	v_pk_fma_f32 v[214:215], v[200:201], v[120:121], v[210:211]
	v_pk_fma_f32 v[214:215], v[184:185], v[212:213], v[214:215]
	v_pk_add_f32 v[214:215], v[208:209], v[214:215]
	v_pk_mul_f32 v[216:217], v[214:215], s[92:93]
	v_pk_mul_f32 v[216:217], v[214:215], v[216:217]
	v_pk_fma_f32 v[216:217], v[214:215], v[216:217], v[214:215]
	v_pk_mul_f32 v[216:217], v[216:217], s[96:97]
	v_pk_mul_f32 v[216:217], v[216:217], s[28:29]
	v_exp_f32_e32 v216, v216
	v_exp_f32_e32 v217, v217
	s_nop 0
	v_add_f32_e32 v216, 1.0, v216
	v_add_f32_e32 v217, 1.0, v217
	v_rcp_f32_e32 v216, v216
	v_rcp_f32_e32 v217, v217
	s_nop 0
	v_pk_mul_f32 v[214:215], v[214:215], v[216:217]
	v_pk_mul_f32 v[214:215], v[128:129], v[214:215]
	v_cvt_pk_bf16_f32 v125, v214, v215
	global_store_dwordx4 v242, v[122:125], s[6:7] offset:3072
	v_mov_b32_dpp v210, v82 row_ror:1 row_mask:0xf bank_mask:0xf
	v_mov_b32_dpp v212, v82 row_ror:2 row_mask:0xf bank_mask:0xf
	v_mov_b32_dpp v211, v83 row_ror:1 row_mask:0xf bank_mask:0xf
	v_mov_b32_dpp v213, v83 row_ror:2 row_mask:0xf bank_mask:0xf
	s_nop 1
	v_mov_b32_dpp v210, v98 row_shr:1 row_mask:0xf bank_mask:0xf
	v_mov_b32_dpp v212, v98 row_shr:2 row_mask:0xf bank_mask:0xf
	v_mov_b32_dpp v211, v99 row_shr:1 row_mask:0xf bank_mask:0xf
	v_mov_b32_dpp v213, v99 row_shr:2 row_mask:0xf bank_mask:0xf
	s_nop 1
	v_pk_mul_f32 v[210:211], v[186:187], v[210:211]
	v_pk_fma_f32 v[214:215], v[194:195], v[98:99], v[210:211]
	v_pk_fma_f32 v[214:215], v[178:179], v[212:213], v[214:215]
	v_pk_add_f32 v[214:215], v[202:203], v[214:215]
	v_pk_mul_f32 v[216:217], v[214:215], s[92:93]
	v_pk_mul_f32 v[216:217], v[214:215], v[216:217]
	v_pk_fma_f32 v[216:217], v[214:215], v[216:217], v[214:215]
	v_pk_mul_f32 v[216:217], v[216:217], s[96:97]
	v_pk_mul_f32 v[216:217], v[216:217], s[28:29]
	v_exp_f32_e32 v216, v216
	v_exp_f32_e32 v217, v217
	s_nop 0
	v_add_f32_e32 v216, 1.0, v216
	v_add_f32_e32 v217, 1.0, v217
	v_rcp_f32_e32 v216, v216
	v_rcp_f32_e32 v217, v217
	s_nop 0
	v_pk_mul_f32 v[214:215], v[214:215], v[216:217]
	v_pk_mul_f32 v[214:215], v[106:107], v[214:215]
	v_cvt_pk_bf16_f32 v106, v214, v215
	v_mov_b32_dpp v210, v84 row_ror:1 row_mask:0xf bank_mask:0xf
	v_mov_b32_dpp v212, v84 row_ror:2 row_mask:0xf bank_mask:0xf
	v_mov_b32_dpp v211, v85 row_ror:1 row_mask:0xf bank_mask:0xf
	v_mov_b32_dpp v213, v85 row_ror:2 row_mask:0xf bank_mask:0xf
	s_nop 1
	v_mov_b32_dpp v210, v100 row_shr:1 row_mask:0xf bank_mask:0xf
	v_mov_b32_dpp v212, v100 row_shr:2 row_mask:0xf bank_mask:0xf
	v_mov_b32_dpp v211, v101 row_shr:1 row_mask:0xf bank_mask:0xf
	v_mov_b32_dpp v213, v101 row_shr:2 row_mask:0xf bank_mask:0xf
	s_nop 1
	v_pk_mul_f32 v[210:211], v[188:189], v[210:211]
	v_pk_fma_f32 v[214:215], v[196:197], v[100:101], v[210:211]
	v_pk_fma_f32 v[214:215], v[180:181], v[212:213], v[214:215]
	v_pk_add_f32 v[214:215], v[204:205], v[214:215]
	v_pk_mul_f32 v[216:217], v[214:215], s[92:93]
	v_pk_mul_f32 v[216:217], v[214:215], v[216:217]
	v_pk_fma_f32 v[216:217], v[214:215], v[216:217], v[214:215]
	v_pk_mul_f32 v[216:217], v[216:217], s[96:97]
	v_pk_mul_f32 v[216:217], v[216:217], s[28:29]
	v_exp_f32_e32 v216, v216
	v_exp_f32_e32 v217, v217
	s_nop 0
	v_add_f32_e32 v216, 1.0, v216
	v_add_f32_e32 v217, 1.0, v217
	v_rcp_f32_e32 v216, v216
	v_rcp_f32_e32 v217, v217
	s_nop 0
	v_pk_mul_f32 v[214:215], v[214:215], v[216:217]
	v_pk_mul_f32 v[214:215], v[108:109], v[214:215]
	v_cvt_pk_bf16_f32 v107, v214, v215
	v_mov_b32_dpp v210, v86 row_ror:1 row_mask:0xf bank_mask:0xf
	v_mov_b32_dpp v212, v86 row_ror:2 row_mask:0xf bank_mask:0xf
	v_mov_b32_dpp v211, v87 row_ror:1 row_mask:0xf bank_mask:0xf
	v_mov_b32_dpp v213, v87 row_ror:2 row_mask:0xf bank_mask:0xf
	s_nop 1
	v_mov_b32_dpp v210, v102 row_shr:1 row_mask:0xf bank_mask:0xf
	v_mov_b32_dpp v212, v102 row_shr:2 row_mask:0xf bank_mask:0xf
	v_mov_b32_dpp v211, v103 row_shr:1 row_mask:0xf bank_mask:0xf
	v_mov_b32_dpp v213, v103 row_shr:2 row_mask:0xf bank_mask:0xf
	s_nop 1
	v_pk_mul_f32 v[210:211], v[190:191], v[210:211]
	v_pk_fma_f32 v[214:215], v[198:199], v[102:103], v[210:211]
	v_pk_fma_f32 v[214:215], v[182:183], v[212:213], v[214:215]
	v_pk_add_f32 v[214:215], v[206:207], v[214:215]
	v_pk_mul_f32 v[216:217], v[214:215], s[92:93]
	v_pk_mul_f32 v[216:217], v[214:215], v[216:217]
	v_pk_fma_f32 v[216:217], v[214:215], v[216:217], v[214:215]
	v_pk_mul_f32 v[216:217], v[216:217], s[96:97]
	v_pk_mul_f32 v[216:217], v[216:217], s[28:29]
	v_exp_f32_e32 v216, v216
	v_exp_f32_e32 v217, v217
	s_nop 0
	v_add_f32_e32 v216, 1.0, v216
	v_add_f32_e32 v217, 1.0, v217
	v_rcp_f32_e32 v216, v216
	v_rcp_f32_e32 v217, v217
	s_nop 0
	v_pk_mul_f32 v[214:215], v[214:215], v[216:217]
	v_pk_mul_f32 v[214:215], v[110:111], v[214:215]
	v_cvt_pk_bf16_f32 v108, v214, v215
	v_mov_b32_dpp v210, v88 row_ror:1 row_mask:0xf bank_mask:0xf
	v_mov_b32_dpp v212, v88 row_ror:2 row_mask:0xf bank_mask:0xf
	v_mov_b32_dpp v211, v89 row_ror:1 row_mask:0xf bank_mask:0xf
	v_mov_b32_dpp v213, v89 row_ror:2 row_mask:0xf bank_mask:0xf
	s_nop 1
	v_mov_b32_dpp v210, v104 row_shr:1 row_mask:0xf bank_mask:0xf
	v_mov_b32_dpp v212, v104 row_shr:2 row_mask:0xf bank_mask:0xf
	v_mov_b32_dpp v211, v105 row_shr:1 row_mask:0xf bank_mask:0xf
	v_mov_b32_dpp v213, v105 row_shr:2 row_mask:0xf bank_mask:0xf
	s_nop 1
	v_pk_mul_f32 v[210:211], v[192:193], v[210:211]
	v_pk_fma_f32 v[214:215], v[200:201], v[104:105], v[210:211]
	v_pk_fma_f32 v[214:215], v[184:185], v[212:213], v[214:215]
	v_pk_add_f32 v[214:215], v[208:209], v[214:215]
	v_pk_mul_f32 v[216:217], v[214:215], s[92:93]
	v_pk_mul_f32 v[216:217], v[214:215], v[216:217]
	v_pk_fma_f32 v[216:217], v[214:215], v[216:217], v[214:215]
	v_pk_mul_f32 v[216:217], v[216:217], s[96:97]
	v_pk_mul_f32 v[216:217], v[216:217], s[28:29]
	v_exp_f32_e32 v216, v216
	v_exp_f32_e32 v217, v217
	s_nop 0
	v_add_f32_e32 v216, 1.0, v216
	v_add_f32_e32 v217, 1.0, v217
	v_rcp_f32_e32 v216, v216
	v_rcp_f32_e32 v217, v217
	s_nop 0
	v_pk_mul_f32 v[214:215], v[214:215], v[216:217]
	v_pk_mul_f32 v[214:215], v[112:113], v[214:215]
	v_cvt_pk_bf16_f32 v109, v214, v215
	global_store_dwordx4 v242, v[106:109], s[6:7] offset:2048
	s_waitcnt vmcnt(2)
	s_barrier
	s_cmp_eq_u32 s41, 2
	s_cbranch_scc0 .Lup_en_nf
	s_add_i32 s27, s34, 0xfffff600
	s_add_i32 s26, s34, 0x3600
	s_cmpk_lt_u32 s34, 0xa00
	s_cselect_b32 s27, s26, s27
	v_mov_b32_e32 v249, s27
	v_mov_b32_e32 v250, s20
	s_mov_b64 s[26:27], exec
	s_mov_b64 exec, 1
	global_store_byte v249, v250, s[64:65] sc0 sc1
	s_mov_b64 exec, s[26:27]
.Lup_en_nf:
	v_mov_b32_dpp v210, v66 row_ror:1 row_mask:0xf bank_mask:0xf
	v_mov_b32_dpp v212, v66 row_ror:2 row_mask:0xf bank_mask:0xf
	v_mov_b32_dpp v211, v67 row_ror:1 row_mask:0xf bank_mask:0xf
	v_mov_b32_dpp v213, v67 row_ror:2 row_mask:0xf bank_mask:0xf
	s_nop 1
	v_mov_b32_dpp v210, v82 row_shr:1 row_mask:0xf bank_mask:0xf
	v_mov_b32_dpp v212, v82 row_shr:2 row_mask:0xf bank_mask:0xf
	v_mov_b32_dpp v211, v83 row_shr:1 row_mask:0xf bank_mask:0xf
	v_mov_b32_dpp v213, v83 row_shr:2 row_mask:0xf bank_mask:0xf
	s_nop 1
	v_pk_mul_f32 v[210:211], v[186:187], v[210:211]
	v_pk_fma_f32 v[214:215], v[194:195], v[82:83], v[210:211]
	v_pk_fma_f32 v[214:215], v[178:179], v[212:213], v[214:215]
	v_pk_add_f32 v[214:215], v[202:203], v[214:215]
	v_pk_mul_f32 v[216:217], v[214:215], s[92:93]
	v_pk_mul_f32 v[216:217], v[214:215], v[216:217]
	v_pk_fma_f32 v[216:217], v[214:215], v[216:217], v[214:215]
	v_pk_mul_f32 v[216:217], v[216:217], s[96:97]
	v_pk_mul_f32 v[216:217], v[216:217], s[28:29]
	v_exp_f32_e32 v216, v216
	v_exp_f32_e32 v217, v217
	s_nop 0
	v_add_f32_e32 v216, 1.0, v216
	v_add_f32_e32 v217, 1.0, v217
	v_rcp_f32_e32 v216, v216
	v_rcp_f32_e32 v217, v217
	s_nop 0
	v_pk_mul_f32 v[214:215], v[214:215], v[216:217]
	v_pk_mul_f32 v[214:215], v[90:91], v[214:215]
	v_cvt_pk_bf16_f32 v90, v214, v215
	v_mov_b32_dpp v210, v68 row_ror:1 row_mask:0xf bank_mask:0xf
	v_mov_b32_dpp v212, v68 row_ror:2 row_mask:0xf bank_mask:0xf
	v_mov_b32_dpp v211, v69 row_ror:1 row_mask:0xf bank_mask:0xf
	v_mov_b32_dpp v213, v69 row_ror:2 row_mask:0xf bank_mask:0xf
	s_nop 1
	v_mov_b32_dpp v210, v84 row_shr:1 row_mask:0xf bank_mask:0xf
	v_mov_b32_dpp v212, v84 row_shr:2 row_mask:0xf bank_mask:0xf
	v_mov_b32_dpp v211, v85 row_shr:1 row_mask:0xf bank_mask:0xf
	v_mov_b32_dpp v213, v85 row_shr:2 row_mask:0xf bank_mask:0xf
	s_nop 1
	v_pk_mul_f32 v[210:211], v[188:189], v[210:211]
	v_pk_fma_f32 v[214:215], v[196:197], v[84:85], v[210:211]
	v_pk_fma_f32 v[214:215], v[180:181], v[212:213], v[214:215]
	v_pk_add_f32 v[214:215], v[204:205], v[214:215]
	v_pk_mul_f32 v[216:217], v[214:215], s[92:93]
	v_pk_mul_f32 v[216:217], v[214:215], v[216:217]
	v_pk_fma_f32 v[216:217], v[214:215], v[216:217], v[214:215]
	v_pk_mul_f32 v[216:217], v[216:217], s[96:97]
	v_pk_mul_f32 v[216:217], v[216:217], s[28:29]
	v_exp_f32_e32 v216, v216
	v_exp_f32_e32 v217, v217
	s_nop 0
	v_add_f32_e32 v216, 1.0, v216
	v_add_f32_e32 v217, 1.0, v217
	v_rcp_f32_e32 v216, v216
	v_rcp_f32_e32 v217, v217
	s_nop 0
	v_pk_mul_f32 v[214:215], v[214:215], v[216:217]
	v_pk_mul_f32 v[214:215], v[92:93], v[214:215]
	v_cvt_pk_bf16_f32 v91, v214, v215
	v_mov_b32_dpp v210, v70 row_ror:1 row_mask:0xf bank_mask:0xf
	v_mov_b32_dpp v212, v70 row_ror:2 row_mask:0xf bank_mask:0xf
	v_mov_b32_dpp v211, v71 row_ror:1 row_mask:0xf bank_mask:0xf
	v_mov_b32_dpp v213, v71 row_ror:2 row_mask:0xf bank_mask:0xf
	s_nop 1
	v_mov_b32_dpp v210, v86 row_shr:1 row_mask:0xf bank_mask:0xf
	v_mov_b32_dpp v212, v86 row_shr:2 row_mask:0xf bank_mask:0xf
	v_mov_b32_dpp v211, v87 row_shr:1 row_mask:0xf bank_mask:0xf
	v_mov_b32_dpp v213, v87 row_shr:2 row_mask:0xf bank_mask:0xf
	s_nop 1
	v_pk_mul_f32 v[210:211], v[190:191], v[210:211]
	v_pk_fma_f32 v[214:215], v[198:199], v[86:87], v[210:211]
	v_pk_fma_f32 v[214:215], v[182:183], v[212:213], v[214:215]
	v_pk_add_f32 v[214:215], v[206:207], v[214:215]
	v_pk_mul_f32 v[216:217], v[214:215], s[92:93]
	v_pk_mul_f32 v[216:217], v[214:215], v[216:217]
	v_pk_fma_f32 v[216:217], v[214:215], v[216:217], v[214:215]
	v_pk_mul_f32 v[216:217], v[216:217], s[96:97]
	v_pk_mul_f32 v[216:217], v[216:217], s[28:29]
	v_exp_f32_e32 v216, v216
	v_exp_f32_e32 v217, v217
	s_nop 0
	v_add_f32_e32 v216, 1.0, v216
	v_add_f32_e32 v217, 1.0, v217
	v_rcp_f32_e32 v216, v216
	v_rcp_f32_e32 v217, v217
	s_nop 0
	v_pk_mul_f32 v[214:215], v[214:215], v[216:217]
	v_pk_mul_f32 v[214:215], v[94:95], v[214:215]
	v_cvt_pk_bf16_f32 v92, v214, v215
	v_mov_b32_dpp v210, v72 row_ror:1 row_mask:0xf bank_mask:0xf
	v_mov_b32_dpp v212, v72 row_ror:2 row_mask:0xf bank_mask:0xf
	v_mov_b32_dpp v211, v73 row_ror:1 row_mask:0xf bank_mask:0xf
	v_mov_b32_dpp v213, v73 row_ror:2 row_mask:0xf bank_mask:0xf
	s_nop 1
	v_mov_b32_dpp v210, v88 row_shr:1 row_mask:0xf bank_mask:0xf
	v_mov_b32_dpp v212, v88 row_shr:2 row_mask:0xf bank_mask:0xf
	v_mov_b32_dpp v211, v89 row_shr:1 row_mask:0xf bank_mask:0xf
	v_mov_b32_dpp v213, v89 row_shr:2 row_mask:0xf bank_mask:0xf
	s_nop 1
	v_pk_mul_f32 v[210:211], v[192:193], v[210:211]
	v_pk_fma_f32 v[214:215], v[200:201], v[88:89], v[210:211]
	v_pk_fma_f32 v[214:215], v[184:185], v[212:213], v[214:215]
	v_pk_add_f32 v[214:215], v[208:209], v[214:215]
	v_pk_mul_f32 v[216:217], v[214:215], s[92:93]
	v_pk_mul_f32 v[216:217], v[214:215], v[216:217]
	v_pk_fma_f32 v[216:217], v[214:215], v[216:217], v[214:215]
	v_pk_mul_f32 v[216:217], v[216:217], s[96:97]
	v_pk_mul_f32 v[216:217], v[216:217], s[28:29]
	v_exp_f32_e32 v216, v216
	v_exp_f32_e32 v217, v217
	s_nop 0
	v_add_f32_e32 v216, 1.0, v216
	v_add_f32_e32 v217, 1.0, v217
	v_rcp_f32_e32 v216, v216
	v_rcp_f32_e32 v217, v217
	s_nop 0
	v_pk_mul_f32 v[214:215], v[214:215], v[216:217]
	v_pk_mul_f32 v[214:215], v[96:97], v[214:215]
	v_cvt_pk_bf16_f32 v93, v214, v215
	global_store_dwordx4 v242, v[90:93], s[6:7] offset:1024
	v_mov_b32_dpp v210, v50 row_ror:1 row_mask:0xf bank_mask:0xf
	v_mov_b32_dpp v212, v50 row_ror:2 row_mask:0xf bank_mask:0xf
	v_mov_b32_dpp v211, v51 row_ror:1 row_mask:0xf bank_mask:0xf
	v_mov_b32_dpp v213, v51 row_ror:2 row_mask:0xf bank_mask:0xf
	s_nop 1
	v_mov_b32_dpp v210, v66 row_shr:1 row_mask:0xf bank_mask:0xf
	v_mov_b32_dpp v212, v66 row_shr:2 row_mask:0xf bank_mask:0xf
	v_mov_b32_dpp v211, v67 row_shr:1 row_mask:0xf bank_mask:0xf
	v_mov_b32_dpp v213, v67 row_shr:2 row_mask:0xf bank_mask:0xf
	s_nop 1
	v_pk_mul_f32 v[210:211], v[186:187], v[210:211]
	v_pk_fma_f32 v[214:215], v[194:195], v[66:67], v[210:211]
	v_pk_fma_f32 v[214:215], v[178:179], v[212:213], v[214:215]
	v_pk_add_f32 v[214:215], v[202:203], v[214:215]
	v_pk_mul_f32 v[216:217], v[214:215], s[92:93]
	v_pk_mul_f32 v[216:217], v[214:215], v[216:217]
	v_pk_fma_f32 v[216:217], v[214:215], v[216:217], v[214:215]
	v_pk_mul_f32 v[216:217], v[216:217], s[96:97]
	v_pk_mul_f32 v[216:217], v[216:217], s[28:29]
	v_exp_f32_e32 v216, v216
	v_exp_f32_e32 v217, v217
	s_nop 0
	v_add_f32_e32 v216, 1.0, v216
	v_add_f32_e32 v217, 1.0, v217
	v_rcp_f32_e32 v216, v216
	v_rcp_f32_e32 v217, v217
	s_nop 0
	v_pk_mul_f32 v[214:215], v[214:215], v[216:217]
	v_pk_mul_f32 v[214:215], v[74:75], v[214:215]
	v_cvt_pk_bf16_f32 v74, v214, v215
	v_mov_b32_dpp v210, v52 row_ror:1 row_mask:0xf bank_mask:0xf
	v_mov_b32_dpp v212, v52 row_ror:2 row_mask:0xf bank_mask:0xf
	v_mov_b32_dpp v211, v53 row_ror:1 row_mask:0xf bank_mask:0xf
	v_mov_b32_dpp v213, v53 row_ror:2 row_mask:0xf bank_mask:0xf
	s_nop 1
	v_mov_b32_dpp v210, v68 row_shr:1 row_mask:0xf bank_mask:0xf
	v_mov_b32_dpp v212, v68 row_shr:2 row_mask:0xf bank_mask:0xf
	v_mov_b32_dpp v211, v69 row_shr:1 row_mask:0xf bank_mask:0xf
	v_mov_b32_dpp v213, v69 row_shr:2 row_mask:0xf bank_mask:0xf
	s_nop 1
	v_pk_mul_f32 v[210:211], v[188:189], v[210:211]
	v_pk_fma_f32 v[214:215], v[196:197], v[68:69], v[210:211]
	v_pk_fma_f32 v[214:215], v[180:181], v[212:213], v[214:215]
	v_pk_add_f32 v[214:215], v[204:205], v[214:215]
	v_pk_mul_f32 v[216:217], v[214:215], s[92:93]
	v_pk_mul_f32 v[216:217], v[214:215], v[216:217]
	v_pk_fma_f32 v[216:217], v[214:215], v[216:217], v[214:215]
	v_pk_mul_f32 v[216:217], v[216:217], s[96:97]
	v_pk_mul_f32 v[216:217], v[216:217], s[28:29]
	v_exp_f32_e32 v216, v216
	v_exp_f32_e32 v217, v217
	s_nop 0
	v_add_f32_e32 v216, 1.0, v216
	v_add_f32_e32 v217, 1.0, v217
	v_rcp_f32_e32 v216, v216
	v_rcp_f32_e32 v217, v217
	s_nop 0
	v_pk_mul_f32 v[214:215], v[214:215], v[216:217]
	v_pk_mul_f32 v[214:215], v[76:77], v[214:215]
	v_cvt_pk_bf16_f32 v75, v214, v215
	v_mov_b32_dpp v210, v54 row_ror:1 row_mask:0xf bank_mask:0xf
	v_mov_b32_dpp v212, v54 row_ror:2 row_mask:0xf bank_mask:0xf
	v_mov_b32_dpp v211, v55 row_ror:1 row_mask:0xf bank_mask:0xf
	v_mov_b32_dpp v213, v55 row_ror:2 row_mask:0xf bank_mask:0xf
	s_nop 1
	v_mov_b32_dpp v210, v70 row_shr:1 row_mask:0xf bank_mask:0xf
	v_mov_b32_dpp v212, v70 row_shr:2 row_mask:0xf bank_mask:0xf
	v_mov_b32_dpp v211, v71 row_shr:1 row_mask:0xf bank_mask:0xf
	v_mov_b32_dpp v213, v71 row_shr:2 row_mask:0xf bank_mask:0xf
	s_nop 1
	v_pk_mul_f32 v[210:211], v[190:191], v[210:211]
	v_pk_fma_f32 v[214:215], v[198:199], v[70:71], v[210:211]
	v_pk_fma_f32 v[214:215], v[182:183], v[212:213], v[214:215]
	v_pk_add_f32 v[214:215], v[206:207], v[214:215]
	v_pk_mul_f32 v[216:217], v[214:215], s[92:93]
	v_pk_mul_f32 v[216:217], v[214:215], v[216:217]
	v_pk_fma_f32 v[216:217], v[214:215], v[216:217], v[214:215]
	v_pk_mul_f32 v[216:217], v[216:217], s[96:97]
	v_pk_mul_f32 v[216:217], v[216:217], s[28:29]
	v_exp_f32_e32 v216, v216
	v_exp_f32_e32 v217, v217
	s_nop 0
	v_add_f32_e32 v216, 1.0, v216
	v_add_f32_e32 v217, 1.0, v217
	v_rcp_f32_e32 v216, v216
	v_rcp_f32_e32 v217, v217
	s_nop 0
	v_pk_mul_f32 v[214:215], v[214:215], v[216:217]
	v_pk_mul_f32 v[214:215], v[78:79], v[214:215]
	v_cvt_pk_bf16_f32 v76, v214, v215
	v_mov_b32_dpp v210, v56 row_ror:1 row_mask:0xf bank_mask:0xf
	v_mov_b32_dpp v212, v56 row_ror:2 row_mask:0xf bank_mask:0xf
	v_mov_b32_dpp v211, v57 row_ror:1 row_mask:0xf bank_mask:0xf
	v_mov_b32_dpp v213, v57 row_ror:2 row_mask:0xf bank_mask:0xf
	s_nop 1
	v_mov_b32_dpp v210, v72 row_shr:1 row_mask:0xf bank_mask:0xf
	v_mov_b32_dpp v212, v72 row_shr:2 row_mask:0xf bank_mask:0xf
	v_mov_b32_dpp v211, v73 row_shr:1 row_mask:0xf bank_mask:0xf
	v_mov_b32_dpp v213, v73 row_shr:2 row_mask:0xf bank_mask:0xf
	s_nop 1
	v_pk_mul_f32 v[210:211], v[192:193], v[210:211]
	v_pk_fma_f32 v[214:215], v[200:201], v[72:73], v[210:211]
	v_pk_fma_f32 v[214:215], v[184:185], v[212:213], v[214:215]
	v_pk_add_f32 v[214:215], v[208:209], v[214:215]
	v_pk_mul_f32 v[216:217], v[214:215], s[92:93]
	v_pk_mul_f32 v[216:217], v[214:215], v[216:217]
	v_pk_fma_f32 v[216:217], v[214:215], v[216:217], v[214:215]
	v_pk_mul_f32 v[216:217], v[216:217], s[96:97]
	v_pk_mul_f32 v[216:217], v[216:217], s[28:29]
	v_exp_f32_e32 v216, v216
	v_exp_f32_e32 v217, v217
	s_nop 0
	v_add_f32_e32 v216, 1.0, v216
	v_add_f32_e32 v217, 1.0, v217
	v_rcp_f32_e32 v216, v216
	v_rcp_f32_e32 v217, v217
	s_nop 0
	v_pk_mul_f32 v[214:215], v[214:215], v[216:217]
	v_pk_mul_f32 v[214:215], v[80:81], v[214:215]
	v_cvt_pk_bf16_f32 v77, v214, v215
	global_store_dwordx4 v242, v[74:77], s[6:7]
	v_mov_b32_dpp v210, v34 row_ror:1 row_mask:0xf bank_mask:0xf
	v_mov_b32_dpp v212, v34 row_ror:2 row_mask:0xf bank_mask:0xf
	v_mov_b32_dpp v211, v35 row_ror:1 row_mask:0xf bank_mask:0xf
	v_mov_b32_dpp v213, v35 row_ror:2 row_mask:0xf bank_mask:0xf
	s_nop 1
	v_mov_b32_dpp v210, v50 row_shr:1 row_mask:0xf bank_mask:0xf
	v_mov_b32_dpp v212, v50 row_shr:2 row_mask:0xf bank_mask:0xf
	v_mov_b32_dpp v211, v51 row_shr:1 row_mask:0xf bank_mask:0xf
	v_mov_b32_dpp v213, v51 row_shr:2 row_mask:0xf bank_mask:0xf
	s_nop 1
	v_pk_mul_f32 v[210:211], v[186:187], v[210:211]
	v_pk_fma_f32 v[214:215], v[194:195], v[50:51], v[210:211]
	v_pk_fma_f32 v[214:215], v[178:179], v[212:213], v[214:215]
	v_pk_add_f32 v[214:215], v[202:203], v[214:215]
	v_pk_mul_f32 v[216:217], v[214:215], s[92:93]
	v_pk_mul_f32 v[216:217], v[214:215], v[216:217]
	v_pk_fma_f32 v[216:217], v[214:215], v[216:217], v[214:215]
	v_pk_mul_f32 v[216:217], v[216:217], s[96:97]
	v_pk_mul_f32 v[216:217], v[216:217], s[28:29]
	v_exp_f32_e32 v216, v216
	v_exp_f32_e32 v217, v217
	s_nop 0
	v_add_f32_e32 v216, 1.0, v216
	v_add_f32_e32 v217, 1.0, v217
	v_rcp_f32_e32 v216, v216
	v_rcp_f32_e32 v217, v217
	s_nop 0
	v_pk_mul_f32 v[214:215], v[214:215], v[216:217]
	v_pk_mul_f32 v[214:215], v[58:59], v[214:215]
	v_cvt_pk_bf16_f32 v58, v214, v215
	v_mov_b32_dpp v210, v36 row_ror:1 row_mask:0xf bank_mask:0xf
	v_mov_b32_dpp v212, v36 row_ror:2 row_mask:0xf bank_mask:0xf
	v_mov_b32_dpp v211, v37 row_ror:1 row_mask:0xf bank_mask:0xf
	v_mov_b32_dpp v213, v37 row_ror:2 row_mask:0xf bank_mask:0xf
	s_nop 1
	v_mov_b32_dpp v210, v52 row_shr:1 row_mask:0xf bank_mask:0xf
	v_mov_b32_dpp v212, v52 row_shr:2 row_mask:0xf bank_mask:0xf
	v_mov_b32_dpp v211, v53 row_shr:1 row_mask:0xf bank_mask:0xf
	v_mov_b32_dpp v213, v53 row_shr:2 row_mask:0xf bank_mask:0xf
	s_nop 1
	v_pk_mul_f32 v[210:211], v[188:189], v[210:211]
	v_pk_fma_f32 v[214:215], v[196:197], v[52:53], v[210:211]
	v_pk_fma_f32 v[214:215], v[180:181], v[212:213], v[214:215]
	v_pk_add_f32 v[214:215], v[204:205], v[214:215]
	v_pk_mul_f32 v[216:217], v[214:215], s[92:93]
	v_pk_mul_f32 v[216:217], v[214:215], v[216:217]
	v_pk_fma_f32 v[216:217], v[214:215], v[216:217], v[214:215]
	v_pk_mul_f32 v[216:217], v[216:217], s[96:97]
	v_pk_mul_f32 v[216:217], v[216:217], s[28:29]
	v_exp_f32_e32 v216, v216
	v_exp_f32_e32 v217, v217
	s_nop 0
	v_add_f32_e32 v216, 1.0, v216
	v_add_f32_e32 v217, 1.0, v217
	v_rcp_f32_e32 v216, v216
	v_rcp_f32_e32 v217, v217
	s_nop 0
	v_pk_mul_f32 v[214:215], v[214:215], v[216:217]
	v_pk_mul_f32 v[214:215], v[60:61], v[214:215]
	v_cvt_pk_bf16_f32 v59, v214, v215
	v_mov_b32_dpp v210, v38 row_ror:1 row_mask:0xf bank_mask:0xf
	v_mov_b32_dpp v212, v38 row_ror:2 row_mask:0xf bank_mask:0xf
	v_mov_b32_dpp v211, v39 row_ror:1 row_mask:0xf bank_mask:0xf
	v_mov_b32_dpp v213, v39 row_ror:2 row_mask:0xf bank_mask:0xf
	s_nop 1
	v_mov_b32_dpp v210, v54 row_shr:1 row_mask:0xf bank_mask:0xf
	v_mov_b32_dpp v212, v54 row_shr:2 row_mask:0xf bank_mask:0xf
	v_mov_b32_dpp v211, v55 row_shr:1 row_mask:0xf bank_mask:0xf
	v_mov_b32_dpp v213, v55 row_shr:2 row_mask:0xf bank_mask:0xf
	s_nop 1
	v_pk_mul_f32 v[210:211], v[190:191], v[210:211]
	v_pk_fma_f32 v[214:215], v[198:199], v[54:55], v[210:211]
	v_pk_fma_f32 v[214:215], v[182:183], v[212:213], v[214:215]
	v_pk_add_f32 v[214:215], v[206:207], v[214:215]
	v_pk_mul_f32 v[216:217], v[214:215], s[92:93]
	v_pk_mul_f32 v[216:217], v[214:215], v[216:217]
	v_pk_fma_f32 v[216:217], v[214:215], v[216:217], v[214:215]
	v_pk_mul_f32 v[216:217], v[216:217], s[96:97]
	v_pk_mul_f32 v[216:217], v[216:217], s[28:29]
	v_exp_f32_e32 v216, v216
	v_exp_f32_e32 v217, v217
	s_nop 0
	v_add_f32_e32 v216, 1.0, v216
	v_add_f32_e32 v217, 1.0, v217
	v_rcp_f32_e32 v216, v216
	v_rcp_f32_e32 v217, v217
	s_nop 0
	v_pk_mul_f32 v[214:215], v[214:215], v[216:217]
	v_pk_mul_f32 v[214:215], v[62:63], v[214:215]
	v_cvt_pk_bf16_f32 v60, v214, v215
	v_mov_b32_dpp v210, v40 row_ror:1 row_mask:0xf bank_mask:0xf
	v_mov_b32_dpp v212, v40 row_ror:2 row_mask:0xf bank_mask:0xf
	v_mov_b32_dpp v211, v41 row_ror:1 row_mask:0xf bank_mask:0xf
	v_mov_b32_dpp v213, v41 row_ror:2 row_mask:0xf bank_mask:0xf
	s_nop 1
	v_mov_b32_dpp v210, v56 row_shr:1 row_mask:0xf bank_mask:0xf
	v_mov_b32_dpp v212, v56 row_shr:2 row_mask:0xf bank_mask:0xf
	v_mov_b32_dpp v211, v57 row_shr:1 row_mask:0xf bank_mask:0xf
	v_mov_b32_dpp v213, v57 row_shr:2 row_mask:0xf bank_mask:0xf
	s_nop 1
	v_pk_mul_f32 v[210:211], v[192:193], v[210:211]
	v_pk_fma_f32 v[214:215], v[200:201], v[56:57], v[210:211]
	v_pk_fma_f32 v[214:215], v[184:185], v[212:213], v[214:215]
	v_pk_add_f32 v[214:215], v[208:209], v[214:215]
	v_pk_mul_f32 v[216:217], v[214:215], s[92:93]
	v_pk_mul_f32 v[216:217], v[214:215], v[216:217]
	v_pk_fma_f32 v[216:217], v[214:215], v[216:217], v[214:215]
	v_pk_mul_f32 v[216:217], v[216:217], s[96:97]
	v_pk_mul_f32 v[216:217], v[216:217], s[28:29]
	v_exp_f32_e32 v216, v216
	v_exp_f32_e32 v217, v217
	s_nop 0
	v_add_f32_e32 v216, 1.0, v216
	v_add_f32_e32 v217, 1.0, v217
	v_rcp_f32_e32 v216, v216
	v_rcp_f32_e32 v217, v217
	s_nop 0
	v_pk_mul_f32 v[214:215], v[214:215], v[216:217]
	v_pk_mul_f32 v[214:215], v[64:65], v[214:215]
	v_cvt_pk_bf16_f32 v61, v214, v215
	global_store_dwordx4 v242, v[58:61], s[18:19] offset:3072
	v_mov_b32_dpp v210, v18 row_ror:1 row_mask:0xf bank_mask:0xf
	v_mov_b32_dpp v212, v18 row_ror:2 row_mask:0xf bank_mask:0xf
	v_mov_b32_dpp v211, v19 row_ror:1 row_mask:0xf bank_mask:0xf
	v_mov_b32_dpp v213, v19 row_ror:2 row_mask:0xf bank_mask:0xf
	s_nop 1
	v_mov_b32_dpp v210, v34 row_shr:1 row_mask:0xf bank_mask:0xf
	v_mov_b32_dpp v212, v34 row_shr:2 row_mask:0xf bank_mask:0xf
	v_mov_b32_dpp v211, v35 row_shr:1 row_mask:0xf bank_mask:0xf
	v_mov_b32_dpp v213, v35 row_shr:2 row_mask:0xf bank_mask:0xf
	s_nop 1
	v_pk_mul_f32 v[210:211], v[186:187], v[210:211]
	v_pk_fma_f32 v[214:215], v[194:195], v[34:35], v[210:211]
	v_pk_fma_f32 v[214:215], v[178:179], v[212:213], v[214:215]
	v_pk_add_f32 v[214:215], v[202:203], v[214:215]
	v_pk_mul_f32 v[216:217], v[214:215], s[92:93]
	v_pk_mul_f32 v[216:217], v[214:215], v[216:217]
	v_pk_fma_f32 v[216:217], v[214:215], v[216:217], v[214:215]
	v_pk_mul_f32 v[216:217], v[216:217], s[96:97]
	v_pk_mul_f32 v[216:217], v[216:217], s[28:29]
	v_exp_f32_e32 v216, v216
	v_exp_f32_e32 v217, v217
	s_nop 0
	v_add_f32_e32 v216, 1.0, v216
	v_add_f32_e32 v217, 1.0, v217
	v_rcp_f32_e32 v216, v216
	v_rcp_f32_e32 v217, v217
	s_nop 0
	v_pk_mul_f32 v[214:215], v[214:215], v[216:217]
	v_pk_mul_f32 v[214:215], v[42:43], v[214:215]
	v_cvt_pk_bf16_f32 v42, v214, v215
	v_mov_b32_dpp v210, v20 row_ror:1 row_mask:0xf bank_mask:0xf
	v_mov_b32_dpp v212, v20 row_ror:2 row_mask:0xf bank_mask:0xf
	v_mov_b32_dpp v211, v21 row_ror:1 row_mask:0xf bank_mask:0xf
	v_mov_b32_dpp v213, v21 row_ror:2 row_mask:0xf bank_mask:0xf
	s_nop 1
	v_mov_b32_dpp v210, v36 row_shr:1 row_mask:0xf bank_mask:0xf
	v_mov_b32_dpp v212, v36 row_shr:2 row_mask:0xf bank_mask:0xf
	v_mov_b32_dpp v211, v37 row_shr:1 row_mask:0xf bank_mask:0xf
	v_mov_b32_dpp v213, v37 row_shr:2 row_mask:0xf bank_mask:0xf
	s_nop 1
	v_pk_mul_f32 v[210:211], v[188:189], v[210:211]
	v_pk_fma_f32 v[214:215], v[196:197], v[36:37], v[210:211]
	v_pk_fma_f32 v[214:215], v[180:181], v[212:213], v[214:215]
	v_pk_add_f32 v[214:215], v[204:205], v[214:215]
	v_pk_mul_f32 v[216:217], v[214:215], s[92:93]
	v_pk_mul_f32 v[216:217], v[214:215], v[216:217]
	v_pk_fma_f32 v[216:217], v[214:215], v[216:217], v[214:215]
	v_pk_mul_f32 v[216:217], v[216:217], s[96:97]
	v_pk_mul_f32 v[216:217], v[216:217], s[28:29]
	v_exp_f32_e32 v216, v216
	v_exp_f32_e32 v217, v217
	s_nop 0
	v_add_f32_e32 v216, 1.0, v216
	v_add_f32_e32 v217, 1.0, v217
	v_rcp_f32_e32 v216, v216
	v_rcp_f32_e32 v217, v217
	s_nop 0
	v_pk_mul_f32 v[214:215], v[214:215], v[216:217]
	v_pk_mul_f32 v[214:215], v[44:45], v[214:215]
	v_cvt_pk_bf16_f32 v43, v214, v215
	v_mov_b32_dpp v210, v22 row_ror:1 row_mask:0xf bank_mask:0xf
	v_mov_b32_dpp v212, v22 row_ror:2 row_mask:0xf bank_mask:0xf
	v_mov_b32_dpp v211, v23 row_ror:1 row_mask:0xf bank_mask:0xf
	v_mov_b32_dpp v213, v23 row_ror:2 row_mask:0xf bank_mask:0xf
	s_nop 1
	v_mov_b32_dpp v210, v38 row_shr:1 row_mask:0xf bank_mask:0xf
	v_mov_b32_dpp v212, v38 row_shr:2 row_mask:0xf bank_mask:0xf
	v_mov_b32_dpp v211, v39 row_shr:1 row_mask:0xf bank_mask:0xf
	v_mov_b32_dpp v213, v39 row_shr:2 row_mask:0xf bank_mask:0xf
	s_nop 1
	v_pk_mul_f32 v[210:211], v[190:191], v[210:211]
	v_pk_fma_f32 v[214:215], v[198:199], v[38:39], v[210:211]
	v_pk_fma_f32 v[214:215], v[182:183], v[212:213], v[214:215]
	v_pk_add_f32 v[214:215], v[206:207], v[214:215]
	v_pk_mul_f32 v[216:217], v[214:215], s[92:93]
	v_pk_mul_f32 v[216:217], v[214:215], v[216:217]
	v_pk_fma_f32 v[216:217], v[214:215], v[216:217], v[214:215]
	v_pk_mul_f32 v[216:217], v[216:217], s[96:97]
	v_pk_mul_f32 v[216:217], v[216:217], s[28:29]
	v_exp_f32_e32 v216, v216
	v_exp_f32_e32 v217, v217
	s_nop 0
	v_add_f32_e32 v216, 1.0, v216
	v_add_f32_e32 v217, 1.0, v217
	v_rcp_f32_e32 v216, v216
	v_rcp_f32_e32 v217, v217
	s_nop 0
	v_pk_mul_f32 v[214:215], v[214:215], v[216:217]
	v_pk_mul_f32 v[214:215], v[46:47], v[214:215]
	v_cvt_pk_bf16_f32 v44, v214, v215
	v_mov_b32_dpp v210, v24 row_ror:1 row_mask:0xf bank_mask:0xf
	v_mov_b32_dpp v212, v24 row_ror:2 row_mask:0xf bank_mask:0xf
	v_mov_b32_dpp v211, v25 row_ror:1 row_mask:0xf bank_mask:0xf
	v_mov_b32_dpp v213, v25 row_ror:2 row_mask:0xf bank_mask:0xf
	s_nop 1
	v_mov_b32_dpp v210, v40 row_shr:1 row_mask:0xf bank_mask:0xf
	v_mov_b32_dpp v212, v40 row_shr:2 row_mask:0xf bank_mask:0xf
	v_mov_b32_dpp v211, v41 row_shr:1 row_mask:0xf bank_mask:0xf
	v_mov_b32_dpp v213, v41 row_shr:2 row_mask:0xf bank_mask:0xf
	s_nop 1
	v_pk_mul_f32 v[210:211], v[192:193], v[210:211]
	v_pk_fma_f32 v[214:215], v[200:201], v[40:41], v[210:211]
	v_pk_fma_f32 v[214:215], v[184:185], v[212:213], v[214:215]
	v_pk_add_f32 v[214:215], v[208:209], v[214:215]
	v_pk_mul_f32 v[216:217], v[214:215], s[92:93]
	v_pk_mul_f32 v[216:217], v[214:215], v[216:217]
	v_pk_fma_f32 v[216:217], v[214:215], v[216:217], v[214:215]
	v_pk_mul_f32 v[216:217], v[216:217], s[96:97]
	v_pk_mul_f32 v[216:217], v[216:217], s[28:29]
	v_exp_f32_e32 v216, v216
	v_exp_f32_e32 v217, v217
	s_nop 0
	v_add_f32_e32 v216, 1.0, v216
	v_add_f32_e32 v217, 1.0, v217
	v_rcp_f32_e32 v216, v216
	v_rcp_f32_e32 v217, v217
	s_nop 0
	v_pk_mul_f32 v[214:215], v[214:215], v[216:217]
	v_pk_mul_f32 v[214:215], v[48:49], v[214:215]
	v_cvt_pk_bf16_f32 v45, v214, v215
	global_store_dwordx4 v242, v[42:45], s[18:19] offset:2048
	v_mov_b32_dpp v210, v2 row_ror:1 row_mask:0xf bank_mask:0xf
	v_mov_b32_dpp v212, v2 row_ror:2 row_mask:0xf bank_mask:0xf
	v_mov_b32_dpp v211, v3 row_ror:1 row_mask:0xf bank_mask:0xf
	v_mov_b32_dpp v213, v3 row_ror:2 row_mask:0xf bank_mask:0xf
	s_nop 1
	v_mov_b32_dpp v210, v18 row_shr:1 row_mask:0xf bank_mask:0xf
	v_mov_b32_dpp v212, v18 row_shr:2 row_mask:0xf bank_mask:0xf
	v_mov_b32_dpp v211, v19 row_shr:1 row_mask:0xf bank_mask:0xf
	v_mov_b32_dpp v213, v19 row_shr:2 row_mask:0xf bank_mask:0xf
	s_nop 1
	v_pk_mul_f32 v[210:211], v[186:187], v[210:211]
	v_pk_fma_f32 v[214:215], v[194:195], v[18:19], v[210:211]
	v_pk_fma_f32 v[214:215], v[178:179], v[212:213], v[214:215]
	v_pk_add_f32 v[214:215], v[202:203], v[214:215]
	v_pk_mul_f32 v[216:217], v[214:215], s[92:93]
	v_pk_mul_f32 v[216:217], v[214:215], v[216:217]
	v_pk_fma_f32 v[216:217], v[214:215], v[216:217], v[214:215]
	v_pk_mul_f32 v[216:217], v[216:217], s[96:97]
	v_pk_mul_f32 v[216:217], v[216:217], s[28:29]
	v_exp_f32_e32 v216, v216
	v_exp_f32_e32 v217, v217
	s_nop 0
	v_add_f32_e32 v216, 1.0, v216
	v_add_f32_e32 v217, 1.0, v217
	v_rcp_f32_e32 v216, v216
	v_rcp_f32_e32 v217, v217
	s_nop 0
	v_pk_mul_f32 v[214:215], v[214:215], v[216:217]
	v_pk_mul_f32 v[214:215], v[26:27], v[214:215]
	v_cvt_pk_bf16_f32 v26, v214, v215
	v_mov_b32_dpp v210, v4 row_ror:1 row_mask:0xf bank_mask:0xf
	v_mov_b32_dpp v212, v4 row_ror:2 row_mask:0xf bank_mask:0xf
	v_mov_b32_dpp v211, v5 row_ror:1 row_mask:0xf bank_mask:0xf
	v_mov_b32_dpp v213, v5 row_ror:2 row_mask:0xf bank_mask:0xf
	s_nop 1
	v_mov_b32_dpp v210, v20 row_shr:1 row_mask:0xf bank_mask:0xf
	v_mov_b32_dpp v212, v20 row_shr:2 row_mask:0xf bank_mask:0xf
	v_mov_b32_dpp v211, v21 row_shr:1 row_mask:0xf bank_mask:0xf
	v_mov_b32_dpp v213, v21 row_shr:2 row_mask:0xf bank_mask:0xf
	s_nop 1
	v_pk_mul_f32 v[210:211], v[188:189], v[210:211]
	v_pk_fma_f32 v[214:215], v[196:197], v[20:21], v[210:211]
	v_pk_fma_f32 v[214:215], v[180:181], v[212:213], v[214:215]
	v_pk_add_f32 v[214:215], v[204:205], v[214:215]
	v_pk_mul_f32 v[216:217], v[214:215], s[92:93]
	v_pk_mul_f32 v[216:217], v[214:215], v[216:217]
	v_pk_fma_f32 v[216:217], v[214:215], v[216:217], v[214:215]
	v_pk_mul_f32 v[216:217], v[216:217], s[96:97]
	v_pk_mul_f32 v[216:217], v[216:217], s[28:29]
	v_exp_f32_e32 v216, v216
	v_exp_f32_e32 v217, v217
	s_nop 0
	v_add_f32_e32 v216, 1.0, v216
	v_add_f32_e32 v217, 1.0, v217
	v_rcp_f32_e32 v216, v216
	v_rcp_f32_e32 v217, v217
	s_nop 0
	v_pk_mul_f32 v[214:215], v[214:215], v[216:217]
	v_pk_mul_f32 v[214:215], v[28:29], v[214:215]
	v_cvt_pk_bf16_f32 v27, v214, v215
	v_mov_b32_dpp v210, v6 row_ror:1 row_mask:0xf bank_mask:0xf
	v_mov_b32_dpp v212, v6 row_ror:2 row_mask:0xf bank_mask:0xf
	v_mov_b32_dpp v211, v7 row_ror:1 row_mask:0xf bank_mask:0xf
	v_mov_b32_dpp v213, v7 row_ror:2 row_mask:0xf bank_mask:0xf
	s_nop 1
	v_mov_b32_dpp v210, v22 row_shr:1 row_mask:0xf bank_mask:0xf
	v_mov_b32_dpp v212, v22 row_shr:2 row_mask:0xf bank_mask:0xf
	v_mov_b32_dpp v211, v23 row_shr:1 row_mask:0xf bank_mask:0xf
	v_mov_b32_dpp v213, v23 row_shr:2 row_mask:0xf bank_mask:0xf
	s_nop 1
	v_pk_mul_f32 v[210:211], v[190:191], v[210:211]
	v_pk_fma_f32 v[214:215], v[198:199], v[22:23], v[210:211]
	v_pk_fma_f32 v[214:215], v[182:183], v[212:213], v[214:215]
	v_pk_add_f32 v[214:215], v[206:207], v[214:215]
	v_pk_mul_f32 v[216:217], v[214:215], s[92:93]
	v_pk_mul_f32 v[216:217], v[214:215], v[216:217]
	v_pk_fma_f32 v[216:217], v[214:215], v[216:217], v[214:215]
	v_pk_mul_f32 v[216:217], v[216:217], s[96:97]
	v_pk_mul_f32 v[216:217], v[216:217], s[28:29]
	v_exp_f32_e32 v216, v216
	v_exp_f32_e32 v217, v217
	s_nop 0
	v_add_f32_e32 v216, 1.0, v216
	v_add_f32_e32 v217, 1.0, v217
	v_rcp_f32_e32 v216, v216
	v_rcp_f32_e32 v217, v217
	s_nop 0
	v_pk_mul_f32 v[214:215], v[214:215], v[216:217]
	v_pk_mul_f32 v[214:215], v[30:31], v[214:215]
	v_cvt_pk_bf16_f32 v28, v214, v215
	v_mov_b32_dpp v210, v8 row_ror:1 row_mask:0xf bank_mask:0xf
	v_mov_b32_dpp v212, v8 row_ror:2 row_mask:0xf bank_mask:0xf
	v_mov_b32_dpp v211, v9 row_ror:1 row_mask:0xf bank_mask:0xf
	v_mov_b32_dpp v213, v9 row_ror:2 row_mask:0xf bank_mask:0xf
	s_nop 1
	v_mov_b32_dpp v210, v24 row_shr:1 row_mask:0xf bank_mask:0xf
	v_mov_b32_dpp v212, v24 row_shr:2 row_mask:0xf bank_mask:0xf
	v_mov_b32_dpp v211, v25 row_shr:1 row_mask:0xf bank_mask:0xf
	v_mov_b32_dpp v213, v25 row_shr:2 row_mask:0xf bank_mask:0xf
	s_nop 1
	v_pk_mul_f32 v[210:211], v[192:193], v[210:211]
	v_pk_fma_f32 v[214:215], v[200:201], v[24:25], v[210:211]
	v_pk_fma_f32 v[214:215], v[184:185], v[212:213], v[214:215]
	v_pk_add_f32 v[214:215], v[208:209], v[214:215]
	v_pk_mul_f32 v[216:217], v[214:215], s[92:93]
	v_pk_mul_f32 v[216:217], v[214:215], v[216:217]
	v_pk_fma_f32 v[216:217], v[214:215], v[216:217], v[214:215]
	v_pk_mul_f32 v[216:217], v[216:217], s[96:97]
	v_pk_mul_f32 v[216:217], v[216:217], s[28:29]
	v_exp_f32_e32 v216, v216
	v_exp_f32_e32 v217, v217
	s_nop 0
	v_add_f32_e32 v216, 1.0, v216
	v_add_f32_e32 v217, 1.0, v217
	v_rcp_f32_e32 v216, v216
	v_rcp_f32_e32 v217, v217
	s_nop 0
	v_pk_mul_f32 v[214:215], v[214:215], v[216:217]
	v_pk_mul_f32 v[214:215], v[32:33], v[214:215]
	v_cvt_pk_bf16_f32 v29, v214, v215
	global_store_dwordx4 v242, v[26:29], s[18:19] offset:1024
	s_cmp_eq_u32 s42, 0
	s_cbranch_scc0 .Lup_en_pv
	s_cmp_eq_u32 s39, 0
	s_cbranch_scc1 .Lup_en_pv
	s_add_i32 s26, s34, -1
	s_add_i32 s27, s26, 0xfffff600
	s_add_i32 s66, s26, 0x3600
	s_cmpk_lt_u32 s26, 0xa00
	s_cselect_b32 s27, s66, s27
	v_mov_b32_e32 v249, s27
	s_lshl_b32 s26, s26, 12
	v_add_u32_e32 v248, s26, v248
	s_mov_b32 s27, 0
.Lup_en_pl:
	global_load_ubyte v250, v249, s[64:65] sc0 sc1
	s_add_i32 s27, s27, 1
	s_waitcnt vmcnt(0)
	v_readfirstlane_b32 s66, v250
	s_cmp_ge_u32 s66, s20
	s_cbranch_scc1 .Lup_en_pg
	s_bitcmp1_b32 s27, 13
	s_cbranch_scc0 .Lup_en_pl
.Lup_en_pg:
	global_load_dwordx4 v[218:221], v248, s[24:25] sc0 sc1
	global_load_dwordx4 v[222:225], v248, s[24:25] offset:16 sc0 sc1
	s_waitcnt vmcnt(0)
.Lup_en_pv:
	v_mov_b32_dpp v210, v218 row_ror:1 row_mask:0xf bank_mask:0xf
	v_mov_b32_dpp v212, v218 row_ror:2 row_mask:0xf bank_mask:0xf
	v_mov_b32_dpp v211, v219 row_ror:1 row_mask:0xf bank_mask:0xf
	v_mov_b32_dpp v213, v219 row_ror:2 row_mask:0xf bank_mask:0xf
	s_nop 1
	v_mov_b32_dpp v210, v2 row_shr:1 row_mask:0xf bank_mask:0xf
	v_mov_b32_dpp v212, v2 row_shr:2 row_mask:0xf bank_mask:0xf
	v_mov_b32_dpp v211, v3 row_shr:1 row_mask:0xf bank_mask:0xf
	v_mov_b32_dpp v213, v3 row_shr:2 row_mask:0xf bank_mask:0xf
	s_nop 1
	v_pk_mul_f32 v[210:211], v[186:187], v[210:211]
	v_pk_fma_f32 v[214:215], v[194:195], v[2:3], v[210:211]
	v_pk_fma_f32 v[214:215], v[178:179], v[212:213], v[214:215]
	v_pk_add_f32 v[214:215], v[202:203], v[214:215]
	v_pk_mul_f32 v[216:217], v[214:215], s[92:93]
	v_pk_mul_f32 v[216:217], v[214:215], v[216:217]
	v_pk_fma_f32 v[216:217], v[214:215], v[216:217], v[214:215]
	v_pk_mul_f32 v[216:217], v[216:217], s[96:97]
	v_pk_mul_f32 v[216:217], v[216:217], s[28:29]
	v_exp_f32_e32 v216, v216
	v_exp_f32_e32 v217, v217
	s_nop 0
	v_add_f32_e32 v216, 1.0, v216
	v_add_f32_e32 v217, 1.0, v217
	v_rcp_f32_e32 v216, v216
	v_rcp_f32_e32 v217, v217
	s_nop 0
	v_pk_mul_f32 v[214:215], v[214:215], v[216:217]
	v_pk_mul_f32 v[214:215], v[10:11], v[214:215]
	v_cvt_pk_bf16_f32 v10, v214, v215
	v_mov_b32_dpp v210, v220 row_ror:1 row_mask:0xf bank_mask:0xf
	v_mov_b32_dpp v212, v220 row_ror:2 row_mask:0xf bank_mask:0xf
	v_mov_b32_dpp v211, v221 row_ror:1 row_mask:0xf bank_mask:0xf
	v_mov_b32_dpp v213, v221 row_ror:2 row_mask:0xf bank_mask:0xf
	s_nop 1
	v_mov_b32_dpp v210, v4 row_shr:1 row_mask:0xf bank_mask:0xf
	v_mov_b32_dpp v212, v4 row_shr:2 row_mask:0xf bank_mask:0xf
	v_mov_b32_dpp v211, v5 row_shr:1 row_mask:0xf bank_mask:0xf
	v_mov_b32_dpp v213, v5 row_shr:2 row_mask:0xf bank_mask:0xf
	s_nop 1
	v_pk_mul_f32 v[210:211], v[188:189], v[210:211]
	v_pk_fma_f32 v[214:215], v[196:197], v[4:5], v[210:211]
	v_pk_fma_f32 v[214:215], v[180:181], v[212:213], v[214:215]
	v_pk_add_f32 v[214:215], v[204:205], v[214:215]
	v_pk_mul_f32 v[216:217], v[214:215], s[92:93]
	v_pk_mul_f32 v[216:217], v[214:215], v[216:217]
	v_pk_fma_f32 v[216:217], v[214:215], v[216:217], v[214:215]
	v_pk_mul_f32 v[216:217], v[216:217], s[96:97]
	v_pk_mul_f32 v[216:217], v[216:217], s[28:29]
	v_exp_f32_e32 v216, v216
	v_exp_f32_e32 v217, v217
	s_nop 0
	v_add_f32_e32 v216, 1.0, v216
	v_add_f32_e32 v217, 1.0, v217
	v_rcp_f32_e32 v216, v216
	v_rcp_f32_e32 v217, v217
	s_nop 0
	v_pk_mul_f32 v[214:215], v[214:215], v[216:217]
	v_pk_mul_f32 v[214:215], v[12:13], v[214:215]
	v_cvt_pk_bf16_f32 v11, v214, v215
	v_mov_b32_dpp v210, v222 row_ror:1 row_mask:0xf bank_mask:0xf
	v_mov_b32_dpp v212, v222 row_ror:2 row_mask:0xf bank_mask:0xf
	v_mov_b32_dpp v211, v223 row_ror:1 row_mask:0xf bank_mask:0xf
	v_mov_b32_dpp v213, v223 row_ror:2 row_mask:0xf bank_mask:0xf
	s_nop 1
	v_mov_b32_dpp v210, v6 row_shr:1 row_mask:0xf bank_mask:0xf
	v_mov_b32_dpp v212, v6 row_shr:2 row_mask:0xf bank_mask:0xf
	v_mov_b32_dpp v211, v7 row_shr:1 row_mask:0xf bank_mask:0xf
	v_mov_b32_dpp v213, v7 row_shr:2 row_mask:0xf bank_mask:0xf
	s_nop 1
	v_pk_mul_f32 v[210:211], v[190:191], v[210:211]
	v_pk_fma_f32 v[214:215], v[198:199], v[6:7], v[210:211]
	v_pk_fma_f32 v[214:215], v[182:183], v[212:213], v[214:215]
	v_pk_add_f32 v[214:215], v[206:207], v[214:215]
	v_pk_mul_f32 v[216:217], v[214:215], s[92:93]
	v_pk_mul_f32 v[216:217], v[214:215], v[216:217]
	v_pk_fma_f32 v[216:217], v[214:215], v[216:217], v[214:215]
	v_pk_mul_f32 v[216:217], v[216:217], s[96:97]
	v_pk_mul_f32 v[216:217], v[216:217], s[28:29]
	v_exp_f32_e32 v216, v216
	v_exp_f32_e32 v217, v217
	s_nop 0
	v_add_f32_e32 v216, 1.0, v216
	v_add_f32_e32 v217, 1.0, v217
	v_rcp_f32_e32 v216, v216
	v_rcp_f32_e32 v217, v217
	s_nop 0
	v_pk_mul_f32 v[214:215], v[214:215], v[216:217]
	v_pk_mul_f32 v[214:215], v[14:15], v[214:215]
	v_cvt_pk_bf16_f32 v12, v214, v215
	v_mov_b32_dpp v210, v224 row_ror:1 row_mask:0xf bank_mask:0xf
	v_mov_b32_dpp v212, v224 row_ror:2 row_mask:0xf bank_mask:0xf
	v_mov_b32_dpp v211, v225 row_ror:1 row_mask:0xf bank_mask:0xf
	v_mov_b32_dpp v213, v225 row_ror:2 row_mask:0xf bank_mask:0xf
	s_nop 1
	v_mov_b32_dpp v210, v8 row_shr:1 row_mask:0xf bank_mask:0xf
	v_mov_b32_dpp v212, v8 row_shr:2 row_mask:0xf bank_mask:0xf
	v_mov_b32_dpp v211, v9 row_shr:1 row_mask:0xf bank_mask:0xf
	v_mov_b32_dpp v213, v9 row_shr:2 row_mask:0xf bank_mask:0xf
	s_nop 1
	v_pk_mul_f32 v[210:211], v[192:193], v[210:211]
	v_pk_fma_f32 v[214:215], v[200:201], v[8:9], v[210:211]
	v_pk_fma_f32 v[214:215], v[184:185], v[212:213], v[214:215]
	v_pk_add_f32 v[214:215], v[208:209], v[214:215]
	v_pk_mul_f32 v[216:217], v[214:215], s[92:93]
	v_pk_mul_f32 v[216:217], v[214:215], v[216:217]
	v_pk_fma_f32 v[216:217], v[214:215], v[216:217], v[214:215]
	v_pk_mul_f32 v[216:217], v[216:217], s[96:97]
	v_pk_mul_f32 v[216:217], v[216:217], s[28:29]
	v_exp_f32_e32 v216, v216
	v_exp_f32_e32 v217, v217
	s_nop 0
	v_add_f32_e32 v216, 1.0, v216
	v_add_f32_e32 v217, 1.0, v217
	v_rcp_f32_e32 v216, v216
	v_rcp_f32_e32 v217, v217
	s_nop 0
	v_pk_mul_f32 v[214:215], v[214:215], v[216:217]
	v_pk_mul_f32 v[214:215], v[16:17], v[214:215]
	v_cvt_pk_bf16_f32 v13, v214, v215
	global_store_dwordx4 v242, v[10:13], s[18:19]
	s_mov_b32 s34, s38
	s_mov_b32 s35, s30
	s_mov_b32 s36, s31
	s_branch .Lup_tile
.Lup_tail_last:
	s_waitcnt vmcnt(6) lgkmcnt(0)
	s_barrier
	v_add_u32_e32 v240, s61, v238
	v_add_u32_e32 v241, s61, v239
	s_add_i32 m0, s60, s62
	v_mfma_f32_16x16x32_bf16 v[2:5], v[162:165], v[130:133], v[2:5]
	global_load_lds_dwordx4 v226, s[54:55]
	v_mfma_f32_16x16x32_bf16 v[6:9], v[166:169], v[130:133], v[6:9]
	global_load_lds_dwordx4 v226, s[54:55] offset:1024
	v_mfma_f32_16x16x32_bf16 v[10:13], v[170:173], v[130:133], v[10:13]
	global_load_lds_dwordx4 v226, s[54:55] offset:2048
	v_mfma_f32_16x16x32_bf16 v[14:17], v[174:177], v[130:133], v[14:17]
	global_load_lds_dwordx4 v226, s[54:55] offset:3072
	s_add_i32 m0, s60, s63
	v_mfma_f32_16x16x32_bf16 v[18:21], v[162:165], v[134:137], v[18:21]
	global_load_lds_dwordx4 v230, s[56:57]
	v_mfma_f32_16x16x32_bf16 v[22:25], v[166:169], v[134:137], v[22:25]
	global_load_lds_dwordx4 v231, s[56:57] offset:1024
	v_mfma_f32_16x16x32_bf16 v[26:29], v[170:173], v[134:137], v[26:29]
	v_mfma_f32_16x16x32_bf16 v[30:33], v[174:177], v[134:137], v[30:33]
	v_mfma_f32_16x16x32_bf16 v[34:37], v[162:165], v[138:141], v[34:37]
	ds_read_b128 v[210:213], v241 offset:0
	v_mfma_f32_16x16x32_bf16 v[38:41], v[166:169], v[138:141], v[38:41]
	ds_read_b128 v[214:217], v241 offset:256
	v_mfma_f32_16x16x32_bf16 v[42:45], v[170:173], v[138:141], v[42:45]
	ds_read_b128 v[218:221], v241 offset:2048
	v_mfma_f32_16x16x32_bf16 v[46:49], v[174:177], v[138:141], v[46:49]
	ds_read_b128 v[222:225], v241 offset:2304
	v_mfma_f32_16x16x32_bf16 v[50:53], v[162:165], v[142:145], v[50:53]
	ds_read_b128 v[178:181], v240 offset:0
	v_mfma_f32_16x16x32_bf16 v[54:57], v[166:169], v[142:145], v[54:57]
	ds_read_b128 v[182:185], v240 offset:1024
	v_mfma_f32_16x16x32_bf16 v[58:61], v[170:173], v[142:145], v[58:61]
	ds_read_b128 v[186:189], v240 offset:2048
	v_mfma_f32_16x16x32_bf16 v[62:65], v[174:177], v[142:145], v[62:65]
	ds_read_b128 v[190:193], v240 offset:3072
	v_mfma_f32_16x16x32_bf16 v[66:69], v[162:165], v[146:149], v[66:69]
	ds_read_b128 v[194:197], v240 offset:4096
	v_mfma_f32_16x16x32_bf16 v[70:73], v[166:169], v[146:149], v[70:73]
	ds_read_b128 v[198:201], v240 offset:5120
	v_mfma_f32_16x16x32_bf16 v[74:77], v[170:173], v[146:149], v[74:77]
	ds_read_b128 v[202:205], v240 offset:6144
	v_mfma_f32_16x16x32_bf16 v[78:81], v[174:177], v[146:149], v[78:81]
	ds_read_b128 v[206:209], v240 offset:7168
	s_setprio 1
	v_mfma_f32_16x16x32_bf16 v[82:85], v[162:165], v[150:153], v[82:85]
	v_mfma_f32_16x16x32_bf16 v[86:89], v[166:169], v[150:153], v[86:89]
	v_mfma_f32_16x16x32_bf16 v[90:93], v[170:173], v[150:153], v[90:93]
	v_mfma_f32_16x16x32_bf16 v[94:97], v[174:177], v[150:153], v[94:97]
	v_mfma_f32_16x16x32_bf16 v[98:101], v[162:165], v[154:157], v[98:101]
	v_mfma_f32_16x16x32_bf16 v[102:105], v[166:169], v[154:157], v[102:105]
	v_mfma_f32_16x16x32_bf16 v[106:109], v[170:173], v[154:157], v[106:109]
	v_mfma_f32_16x16x32_bf16 v[110:113], v[174:177], v[154:157], v[110:113]
	v_mfma_f32_16x16x32_bf16 v[114:117], v[162:165], v[158:161], v[114:117]
	v_mfma_f32_16x16x32_bf16 v[118:121], v[166:169], v[158:161], v[118:121]
	v_mfma_f32_16x16x32_bf16 v[122:125], v[170:173], v[158:161], v[122:125]
	v_mfma_f32_16x16x32_bf16 v[126:129], v[174:177], v[158:161], v[126:129]
	s_setprio 0
	s_add_i32 s60, s60, 0x6000
	s_cmp_eq_u32 s60, 0x12000
	s_cselect_b32 s60, 0, s60
	s_add_u32 s54, s54, s72
	s_addc_u32 s55, s55, 0
	s_add_u32 s56, s56, s73
	s_addc_u32 s57, s57, 0
	s_add_i32 s61, s61, 0x6000
	s_cmp_eq_u32 s61, 0x12000
	s_cselect_b32 s61, 0, s61
	s_waitcnt vmcnt(6) lgkmcnt(0)
	s_barrier
	v_add_u32_e32 v240, s61, v238
	v_add_u32_e32 v241, s61, v239
	v_mfma_f32_16x16x32_bf16 v[2:5], v[210:213], v[178:181], v[2:5]
	v_mfma_f32_16x16x32_bf16 v[6:9], v[214:217], v[178:181], v[6:9]
	v_mfma_f32_16x16x32_bf16 v[10:13], v[218:221], v[178:181], v[10:13]
	v_mfma_f32_16x16x32_bf16 v[14:17], v[222:225], v[178:181], v[14:17]
	v_mfma_f32_16x16x32_bf16 v[18:21], v[210:213], v[182:185], v[18:21]
	v_mfma_f32_16x16x32_bf16 v[22:25], v[214:217], v[182:185], v[22:25]
	v_mfma_f32_16x16x32_bf16 v[26:29], v[218:221], v[182:185], v[26:29]
	v_mfma_f32_16x16x32_bf16 v[30:33], v[222:225], v[182:185], v[30:33]
	v_mfma_f32_16x16x32_bf16 v[34:37], v[210:213], v[186:189], v[34:37]
	ds_read_b128 v[162:165], v241 offset:0
	v_mfma_f32_16x16x32_bf16 v[38:41], v[214:217], v[186:189], v[38:41]
	ds_read_b128 v[166:169], v241 offset:256
	v_mfma_f32_16x16x32_bf16 v[42:45], v[218:221], v[186:189], v[42:45]
	ds_read_b128 v[170:173], v241 offset:2048
	v_mfma_f32_16x16x32_bf16 v[46:49], v[222:225], v[186:189], v[46:49]
	ds_read_b128 v[174:177], v241 offset:2304
	v_mfma_f32_16x16x32_bf16 v[50:53], v[210:213], v[190:193], v[50:53]
	ds_read_b128 v[130:133], v240 offset:0
	v_mfma_f32_16x16x32_bf16 v[54:57], v[214:217], v[190:193], v[54:57]
	ds_read_b128 v[134:137], v240 offset:1024
	v_mfma_f32_16x16x32_bf16 v[58:61], v[218:221], v[190:193], v[58:61]
	ds_read_b128 v[138:141], v240 offset:2048
	v_mfma_f32_16x16x32_bf16 v[62:65], v[222:225], v[190:193], v[62:65]
	ds_read_b128 v[142:145], v240 offset:3072
	v_mfma_f32_16x16x32_bf16 v[66:69], v[210:213], v[194:197], v[66:69]
	ds_read_b128 v[146:149], v240 offset:4096
	v_mfma_f32_16x16x32_bf16 v[70:73], v[214:217], v[194:197], v[70:73]
	ds_read_b128 v[150:153], v240 offset:5120
	v_mfma_f32_16x16x32_bf16 v[74:77], v[218:221], v[194:197], v[74:77]
	ds_read_b128 v[154:157], v240 offset:6144
	v_mfma_f32_16x16x32_bf16 v[78:81], v[222:225], v[194:197], v[78:81]
	ds_read_b128 v[158:161], v240 offset:7168
	s_setprio 1
	v_mfma_f32_16x16x32_bf16 v[82:85], v[210:213], v[198:201], v[82:85]
	v_mfma_f32_16x16x32_bf16 v[86:89], v[214:217], v[198:201], v[86:89]
	v_mfma_f32_16x16x32_bf16 v[90:93], v[218:221], v[198:201], v[90:93]
	v_mfma_f32_16x16x32_bf16 v[94:97], v[222:225], v[198:201], v[94:97]
	v_mfma_f32_16x16x32_bf16 v[98:101], v[210:213], v[202:205], v[98:101]
	v_mfma_f32_16x16x32_bf16 v[102:105], v[214:217], v[202:205], v[102:105]
	v_mfma_f32_16x16x32_bf16 v[106:109], v[218:221], v[202:205], v[106:109]
	v_mfma_f32_16x16x32_bf16 v[110:113], v[222:225], v[202:205], v[110:113]
	v_mfma_f32_16x16x32_bf16 v[114:117], v[210:213], v[206:209], v[114:117]
	v_mfma_f32_16x16x32_bf16 v[118:121], v[214:217], v[206:209], v[118:121]
	v_mfma_f32_16x16x32_bf16 v[122:125], v[218:221], v[206:209], v[122:125]
	v_mfma_f32_16x16x32_bf16 v[126:129], v[222:225], v[206:209], v[126:129]
	s_setprio 0
	s_add_i32 s61, s61, 0x6000
	s_cmp_eq_u32 s61, 0x12000
	s_cselect_b32 s61, 0, s61
	s_waitcnt vmcnt(0) lgkmcnt(0)
	s_barrier
	v_add_u32_e32 v240, s61, v238
	v_add_u32_e32 v241, s61, v239
	v_mfma_f32_16x16x32_bf16 v[2:5], v[162:165], v[130:133], v[2:5]
	v_mfma_f32_16x16x32_bf16 v[6:9], v[166:169], v[130:133], v[6:9]
	v_mfma_f32_16x16x32_bf16 v[10:13], v[170:173], v[130:133], v[10:13]
	v_mfma_f32_16x16x32_bf16 v[14:17], v[174:177], v[130:133], v[14:17]
	v_mfma_f32_16x16x32_bf16 v[18:21], v[162:165], v[134:137], v[18:21]
	v_mfma_f32_16x16x32_bf16 v[22:25], v[166:169], v[134:137], v[22:25]
	v_mfma_f32_16x16x32_bf16 v[26:29], v[170:173], v[134:137], v[26:29]
	v_mfma_f32_16x16x32_bf16 v[30:33], v[174:177], v[134:137], v[30:33]
	v_mfma_f32_16x16x32_bf16 v[34:37], v[162:165], v[138:141], v[34:37]
	ds_read_b128 v[210:213], v241 offset:0
	v_mfma_f32_16x16x32_bf16 v[38:41], v[166:169], v[138:141], v[38:41]
	ds_read_b128 v[214:217], v241 offset:256
	v_mfma_f32_16x16x32_bf16 v[42:45], v[170:173], v[138:141], v[42:45]
	ds_read_b128 v[218:221], v241 offset:2048
	v_mfma_f32_16x16x32_bf16 v[46:49], v[174:177], v[138:141], v[46:49]
	ds_read_b128 v[222:225], v241 offset:2304
	v_mfma_f32_16x16x32_bf16 v[50:53], v[162:165], v[142:145], v[50:53]
	ds_read_b128 v[178:181], v240 offset:0
	v_mfma_f32_16x16x32_bf16 v[54:57], v[166:169], v[142:145], v[54:57]
	ds_read_b128 v[182:185], v240 offset:1024
	v_mfma_f32_16x16x32_bf16 v[58:61], v[170:173], v[142:145], v[58:61]
	ds_read_b128 v[186:189], v240 offset:2048
	v_mfma_f32_16x16x32_bf16 v[62:65], v[174:177], v[142:145], v[62:65]
	ds_read_b128 v[190:193], v240 offset:3072
	v_mfma_f32_16x16x32_bf16 v[66:69], v[162:165], v[146:149], v[66:69]
	ds_read_b128 v[194:197], v240 offset:4096
	v_mfma_f32_16x16x32_bf16 v[70:73], v[166:169], v[146:149], v[70:73]
	ds_read_b128 v[198:201], v240 offset:5120
	v_mfma_f32_16x16x32_bf16 v[74:77], v[170:173], v[146:149], v[74:77]
	ds_read_b128 v[202:205], v240 offset:6144
	v_mfma_f32_16x16x32_bf16 v[78:81], v[174:177], v[146:149], v[78:81]
	ds_read_b128 v[206:209], v240 offset:7168
	s_setprio 1
	v_mfma_f32_16x16x32_bf16 v[82:85], v[162:165], v[150:153], v[82:85]
	v_mfma_f32_16x16x32_bf16 v[86:89], v[166:169], v[150:153], v[86:89]
	v_mfma_f32_16x16x32_bf16 v[90:93], v[170:173], v[150:153], v[90:93]
	v_mfma_f32_16x16x32_bf16 v[94:97], v[174:177], v[150:153], v[94:97]
	v_mfma_f32_16x16x32_bf16 v[98:101], v[162:165], v[154:157], v[98:101]
	v_mfma_f32_16x16x32_bf16 v[102:105], v[166:169], v[154:157], v[102:105]
	v_mfma_f32_16x16x32_bf16 v[106:109], v[170:173], v[154:157], v[106:109]
	v_mfma_f32_16x16x32_bf16 v[110:113], v[174:177], v[154:157], v[110:113]
	v_mfma_f32_16x16x32_bf16 v[114:117], v[162:165], v[158:161], v[114:117]
	v_mfma_f32_16x16x32_bf16 v[118:121], v[166:169], v[158:161], v[118:121]
	v_mfma_f32_16x16x32_bf16 v[122:125], v[170:173], v[158:161], v[122:125]
	v_mfma_f32_16x16x32_bf16 v[126:129], v[174:177], v[158:161], v[126:129]
	s_setprio 0
	s_add_i32 s61, s61, 0x6000
	s_cmp_eq_u32 s61, 0x12000
	s_cselect_b32 s61, 0, s61
	s_waitcnt lgkmcnt(0)
	s_barrier
	v_mfma_f32_16x16x32_bf16 v[2:5], v[210:213], v[178:181], v[2:5]
	v_mfma_f32_16x16x32_bf16 v[6:9], v[214:217], v[178:181], v[6:9]
	v_mfma_f32_16x16x32_bf16 v[10:13], v[218:221], v[178:181], v[10:13]
	v_mfma_f32_16x16x32_bf16 v[14:17], v[222:225], v[178:181], v[14:17]
	v_mfma_f32_16x16x32_bf16 v[18:21], v[210:213], v[182:185], v[18:21]
	v_mfma_f32_16x16x32_bf16 v[22:25], v[214:217], v[182:185], v[22:25]
	v_mfma_f32_16x16x32_bf16 v[26:29], v[218:221], v[182:185], v[26:29]
	v_mfma_f32_16x16x32_bf16 v[30:33], v[222:225], v[182:185], v[30:33]
	v_mfma_f32_16x16x32_bf16 v[34:37], v[210:213], v[186:189], v[34:37]
	v_mfma_f32_16x16x32_bf16 v[38:41], v[214:217], v[186:189], v[38:41]
	v_mfma_f32_16x16x32_bf16 v[42:45], v[218:221], v[186:189], v[42:45]
	v_mfma_f32_16x16x32_bf16 v[46:49], v[222:225], v[186:189], v[46:49]
	v_mfma_f32_16x16x32_bf16 v[50:53], v[210:213], v[190:193], v[50:53]
	v_mfma_f32_16x16x32_bf16 v[54:57], v[214:217], v[190:193], v[54:57]
	v_mfma_f32_16x16x32_bf16 v[58:61], v[218:221], v[190:193], v[58:61]
	v_mfma_f32_16x16x32_bf16 v[62:65], v[222:225], v[190:193], v[62:65]
	v_mfma_f32_16x16x32_bf16 v[66:69], v[210:213], v[194:197], v[66:69]
	v_mfma_f32_16x16x32_bf16 v[70:73], v[214:217], v[194:197], v[70:73]
	v_mfma_f32_16x16x32_bf16 v[74:77], v[218:221], v[194:197], v[74:77]
	v_mfma_f32_16x16x32_bf16 v[78:81], v[222:225], v[194:197], v[78:81]
	s_setprio 1
	v_mfma_f32_16x16x32_bf16 v[82:85], v[210:213], v[198:201], v[82:85]
	v_mfma_f32_16x16x32_bf16 v[86:89], v[214:217], v[198:201], v[86:89]
	v_mfma_f32_16x16x32_bf16 v[90:93], v[218:221], v[198:201], v[90:93]
	v_mfma_f32_16x16x32_bf16 v[94:97], v[222:225], v[198:201], v[94:97]
	v_mfma_f32_16x16x32_bf16 v[98:101], v[210:213], v[202:205], v[98:101]
	v_mfma_f32_16x16x32_bf16 v[102:105], v[214:217], v[202:205], v[102:105]
	v_mfma_f32_16x16x32_bf16 v[106:109], v[218:221], v[202:205], v[106:109]
	v_mfma_f32_16x16x32_bf16 v[110:113], v[222:225], v[202:205], v[110:113]
	v_mfma_f32_16x16x32_bf16 v[114:117], v[210:213], v[206:209], v[114:117]
	v_mfma_f32_16x16x32_bf16 v[118:121], v[214:217], v[206:209], v[118:121]
	v_mfma_f32_16x16x32_bf16 v[122:125], v[218:221], v[206:209], v[122:125]
	v_mfma_f32_16x16x32_bf16 v[126:129], v[222:225], v[206:209], v[126:129]
	s_setprio 0
	s_and_b32 s39, s35, 0xfff
	s_lshr_b32 s21, s36, 7
	s_waitcnt vmcnt(0)
	v_mbcnt_lo_u32_b32 v217, -1, 0
	v_mbcnt_hi_u32_b32 v217, -1, v217
	v_lshlrev_b32_e32 v217, 5, v217
	s_lshl_b32 s26, s43, 11
	v_add_u32_e32 v248, s26, v217
	s_add_i32 s26, s26, 0x12010
	v_add_u32_e32 v217, s26, v217
	s_cmp_eq_u32 s42, 0
	s_cbranch_scc0 .Lup_el_nowr
	ds_write_b128 v217, v[114:117]
	ds_write_b128 v217, v[118:121] offset:16
	s_branch .Lup_el_wrd

.Lup_el_pv:
	v_mov_b32_dpp v210, v218 row_ror:1 row_mask:0xf bank_mask:0xf
	v_mov_b32_dpp v212, v218 row_ror:2 row_mask:0xf bank_mask:0xf
	v_mov_b32_dpp v211, v219 row_ror:1 row_mask:0xf bank_mask:0xf
	v_mov_b32_dpp v213, v219 row_ror:2 row_mask:0xf bank_mask:0xf
	s_nop 1
	v_mov_b32_dpp v210, v2 row_shr:1 row_mask:0xf bank_mask:0xf
	v_mov_b32_dpp v212, v2 row_shr:2 row_mask:0xf bank_mask:0xf
	v_mov_b32_dpp v211, v3 row_shr:1 row_mask:0xf bank_mask:0xf
	v_mov_b32_dpp v213, v3 row_shr:2 row_mask:0xf bank_mask:0xf
	s_nop 1
	v_pk_mul_f32 v[210:211], v[186:187], v[210:211]
	v_pk_fma_f32 v[214:215], v[194:195], v[2:3], v[210:211]
	v_pk_fma_f32 v[214:215], v[178:179], v[212:213], v[214:215]
	v_pk_add_f32 v[214:215], v[202:203], v[214:215]
	v_pk_mul_f32 v[216:217], v[214:215], s[92:93]
	v_pk_mul_f32 v[216:217], v[214:215], v[216:217]
	v_pk_fma_f32 v[216:217], v[214:215], v[216:217], v[214:215]
	v_pk_mul_f32 v[216:217], v[216:217], s[96:97]
	v_pk_mul_f32 v[216:217], v[216:217], s[28:29]
	v_exp_f32_e32 v216, v216
	v_exp_f32_e32 v217, v217
	s_nop 0
	v_add_f32_e32 v216, 1.0, v216
	v_add_f32_e32 v217, 1.0, v217
	v_rcp_f32_e32 v216, v216
	v_rcp_f32_e32 v217, v217
	s_nop 0
	v_pk_mul_f32 v[214:215], v[214:215], v[216:217]
	v_pk_mul_f32 v[214:215], v[10:11], v[214:215]
	v_cvt_pk_bf16_f32 v10, v214, v215
	v_mov_b32_dpp v210, v220 row_ror:1 row_mask:0xf bank_mask:0xf
	v_mov_b32_dpp v212, v220 row_ror:2 row_mask:0xf bank_mask:0xf
	v_mov_b32_dpp v211, v221 row_ror:1 row_mask:0xf bank_mask:0xf
	v_mov_b32_dpp v213, v221 row_ror:2 row_mask:0xf bank_mask:0xf
	s_nop 1
	v_mov_b32_dpp v210, v4 row_shr:1 row_mask:0xf bank_mask:0xf
	v_mov_b32_dpp v212, v4 row_shr:2 row_mask:0xf bank_mask:0xf
	v_mov_b32_dpp v211, v5 row_shr:1 row_mask:0xf bank_mask:0xf
	v_mov_b32_dpp v213, v5 row_shr:2 row_mask:0xf bank_mask:0xf
	s_nop 1
	v_pk_mul_f32 v[210:211], v[188:189], v[210:211]
	v_pk_fma_f32 v[214:215], v[196:197], v[4:5], v[210:211]
	v_pk_fma_f32 v[214:215], v[180:181], v[212:213], v[214:215]
	v_pk_add_f32 v[214:215], v[204:205], v[214:215]
	v_pk_mul_f32 v[216:217], v[214:215], s[92:93]
	v_pk_mul_f32 v[216:217], v[214:215], v[216:217]
	v_pk_fma_f32 v[216:217], v[214:215], v[216:217], v[214:215]
	v_pk_mul_f32 v[216:217], v[216:217], s[96:97]
	v_pk_mul_f32 v[216:217], v[216:217], s[28:29]
	v_exp_f32_e32 v216, v216
	v_exp_f32_e32 v217, v217
	s_nop 0
	v_add_f32_e32 v216, 1.0, v216
	v_add_f32_e32 v217, 1.0, v217
	v_rcp_f32_e32 v216, v216
	v_rcp_f32_e32 v217, v217
	s_nop 0
	v_pk_mul_f32 v[214:215], v[214:215], v[216:217]
	v_pk_mul_f32 v[214:215], v[12:13], v[214:215]
	v_cvt_pk_bf16_f32 v11, v214, v215
	v_mov_b32_dpp v210, v222 row_ror:1 row_mask:0xf bank_mask:0xf
	v_mov_b32_dpp v212, v222 row_ror:2 row_mask:0xf bank_mask:0xf
	v_mov_b32_dpp v211, v223 row_ror:1 row_mask:0xf bank_mask:0xf
	v_mov_b32_dpp v213, v223 row_ror:2 row_mask:0xf bank_mask:0xf
	s_nop 1
	v_mov_b32_dpp v210, v6 row_shr:1 row_mask:0xf bank_mask:0xf
	v_mov_b32_dpp v212, v6 row_shr:2 row_mask:0xf bank_mask:0xf
	v_mov_b32_dpp v211, v7 row_shr:1 row_mask:0xf bank_mask:0xf
	v_mov_b32_dpp v213, v7 row_shr:2 row_mask:0xf bank_mask:0xf
	s_nop 1
	v_pk_mul_f32 v[210:211], v[190:191], v[210:211]
	v_pk_fma_f32 v[214:215], v[198:199], v[6:7], v[210:211]
	v_pk_fma_f32 v[214:215], v[182:183], v[212:213], v[214:215]
	v_pk_add_f32 v[214:215], v[206:207], v[214:215]
	v_pk_mul_f32 v[216:217], v[214:215], s[92:93]
	v_pk_mul_f32 v[216:217], v[214:215], v[216:217]
	v_pk_fma_f32 v[216:217], v[214:215], v[216:217], v[214:215]
	v_pk_mul_f32 v[216:217], v[216:217], s[96:97]
	v_pk_mul_f32 v[216:217], v[216:217], s[28:29]
	v_exp_f32_e32 v216, v216
	v_exp_f32_e32 v217, v217
	s_nop 0
	v_add_f32_e32 v216, 1.0, v216
	v_add_f32_e32 v217, 1.0, v217
	v_rcp_f32_e32 v216, v216
	v_rcp_f32_e32 v217, v217
	s_nop 0
	v_pk_mul_f32 v[214:215], v[214:215], v[216:217]
	v_pk_mul_f32 v[214:215], v[14:15], v[214:215]
	v_cvt_pk_bf16_f32 v12, v214, v215
	v_mov_b32_dpp v210, v224 row_ror:1 row_mask:0xf bank_mask:0xf
	v_mov_b32_dpp v212, v224 row_ror:2 row_mask:0xf bank_mask:0xf
	v_mov_b32_dpp v211, v225 row_ror:1 row_mask:0xf bank_mask:0xf
	v_mov_b32_dpp v213, v225 row_ror:2 row_mask:0xf bank_mask:0xf
	s_nop 1
	v_mov_b32_dpp v210, v8 row_shr:1 row_mask:0xf bank_mask:0xf
	v_mov_b32_dpp v212, v8 row_shr:2 row_mask:0xf bank_mask:0xf
	v_mov_b32_dpp v211, v9 row_shr:1 row_mask:0xf bank_mask:0xf
	v_mov_b32_dpp v213, v9 row_shr:2 row_mask:0xf bank_mask:0xf
	s_nop 1
	v_pk_mul_f32 v[210:211], v[192:193], v[210:211]
	v_pk_fma_f32 v[214:215], v[200:201], v[8:9], v[210:211]
	v_pk_fma_f32 v[214:215], v[184:185], v[212:213], v[214:215]
	v_pk_add_f32 v[214:215], v[208:209], v[214:215]
	v_pk_mul_f32 v[216:217], v[214:215], s[92:93]
	v_pk_mul_f32 v[216:217], v[214:215], v[216:217]
	v_pk_fma_f32 v[216:217], v[214:215], v[216:217], v[214:215]
	v_pk_mul_f32 v[216:217], v[216:217], s[96:97]
	v_pk_mul_f32 v[216:217], v[216:217], s[28:29]
	v_exp_f32_e32 v216, v216
	v_exp_f32_e32 v217, v217
	s_nop 0
	v_add_f32_e32 v216, 1.0, v216
	v_add_f32_e32 v217, 1.0, v217
	v_rcp_f32_e32 v216, v216
	v_rcp_f32_e32 v217, v217
	s_nop 0
	v_pk_mul_f32 v[214:215], v[214:215], v[216:217]
	v_pk_mul_f32 v[214:215], v[16:17], v[214:215]
	v_cvt_pk_bf16_f32 v13, v214, v215
	global_store_dwordx4 v242, v[10:13], s[18:19]
